# nt (non-temporal) hint on P1/P6/P7 epilogue stores
# baseline (speedup 1.0000x reference)
; #define PG8_STAGE(bufoff, gbase, voff) do { _Pragma("unroll") for (int _i = 0; _i < 2; ++_i) \
;         __builtin_amdgcn_global_load_lds((const unsigned*)((const char*)(gbase) + (voff)[_i]), (PG8_LAS unsigned*)(lds + (bufoff) + ldsw + _i * 8192), 16, 0, 0); } while (0)
; #define PG8_WAIT_V(n) asm volatile("s_waitcnt vmcnt(" #n ")" ::: "memory")
; template <class Epi, class Sched, bool ALIGN_EPI = false, bool SP2 = false>
; __device__ __forceinline__ void gemm_phase(PG8_LAS unsigned char* lds, const Gemm g, const Sched& S, const Epi& E) {
;     ...
;         const bool has_next = S.next(ui + 1, nxt);
;         const char* nA = has_next ? (const char*)g.A + (size_t)nxt.pm * tstep : cA; const char* nB = has_next ? (const char*)g.Bt + (size_t)nxt.pn * tstep : cB;
;         for (int t = 0; t < nt; t += 2) {
;             const bool last = (t == nt - 2);
;             const char* a1 = cA + (size_t)(t + 1) * kstep;
;             const char* a2 = last ? nA : cA + (size_t)(t + 2) * kstep; const char* b2 = last ? nB : cB + (size_t)(t + 2) * kstep;
;             const char* a3 = a2 + kstep; const char* b3 = b2 + kstep;
;             if (last && has_next) S.a_ready(nxt);
;             if constexpr (SP2) {
;             PG8_LDB(B0, 0, 0); PG8_LDB(B1, 0, 1); PG8_SCHED; PG8_LDA(At, 0, 0); PG8_STAGE(PG8_SA(1, 1), a1 + hstep, voffA);
;             PG8_WAIT_V(8); PG8_WAIT_L(0); PG8_BAR; PG8_MMA(0, 0, At, B0); PG8_MMA(0, 1, At, B1); PG8_BAR; PG8_SCHED;
;             PG8_LDA(At, 0, 1); PG8_STAGE(PG8_SB(0, 0), b2, voffB); PG8_STAGE(PG8_SB(0, 1), b2 + hstep, voffB); PG8_STAGE(PG8_SA(0, 0), a2, voffA);
;     __device__ __forceinline__ void operator()(const f32x4 (&acc)[2][2][4][2], const pg8::Unit& u, int wr, int wc, int fr, int fq) const {
;     ...
;             for (int m = 0; m < 4; ++m) {
;                 const int row = row0 + ai * 128 + m * 16;
;                 const float rs = sumsq ? rsqrtf(sumsq[row] * (1.f / 1024.f) + EPS) : 1.f;
;                 float o[8];
; #pragma unroll
;                 for (int n = 0; n < 2; ++n)
; #pragma unroll
;                     for (int e = 0; e < 4; ++e) { const float g = acc[ai][0][m][n][e] * rs, up = acc[ai][1][m][n][e] * rs; o[4 * n + e] = silu_f(g) * up; }
;                 u32x4 w; w.x = pk2(o[0], o[1]); w.y = pk2(o[2], o[3]); w.z = pk2(o[4], o[5]); w.w = pk2(o[6], o[7]);
;                 *(u32x4*)(H + (size_t)row * DFF + col) = w;
.LBB0_191:
	s_ashr_i32 s15, s14, 31
	s_lshl_b64 s[16:17], s[14:15], 19
	v_readlane_b32 s18, v235, 31
	v_readlane_b32 s19, v235, 32
	s_add_u32 s16, s18, s16
	s_addc_u32 s17, s19, s17
	s_and_b64 s[18:19], s[0:1], exec
	s_cselect_b32 s15, s17, s23
	s_cselect_b32 s50, s16, s22
	s_ashr_i32 s9, s8, 31
	s_lshl_b64 s[18:19], s[8:9], 19
	s_add_u32 s18, s33, s18
	s_addc_u32 s19, s34, s19
	s_and_b64 s[30:31], s[0:1], exec
	s_cselect_b32 s9, s19, s25
	s_cselect_b32 s51, s18, s24
	s_add_u32 s22, s22, 0x40080
	s_addc_u32 s23, s23, 0
	s_add_u32 s52, s24, 0x100
	s_addc_u32 s53, s25, 0
	s_mov_b32 s54, -2
	s_cmp_eq_u32 s98, 0
	s_cbranch_scc1 .Lp1_plain
	ds_read_b128 v[150:153], v147
	ds_read_b128 v[154:157], v147 offset:1024
	ds_read_b128 v[158:161], v147 offset:2048
	ds_read_b128 v[162:165], v147 offset:3072
	ds_read_b128 v[166:169], v148
	ds_read_b128 v[170:173], v148 offset:1024
	ds_read_b128 v[174:177], v148 offset:2048
	ds_read_b128 v[178:181], v148 offset:3072
	s_add_u32 s24, s22, 0xfffc0080
	s_addc_u32 s25, s23, -1
	s_cmp_eq_u32 s54, 12
	s_cselect_b32 s31, s15, s25
	s_cselect_b32 s30, s50, s24
	s_cselect_b32 s25, s9, s53
	s_cselect_b32 s24, s51, s52
	v_lshl_add_u64 v[186:187], s[22:23], 0, v[136:137]
	s_add_i32 m0, s21, 0xc000
	ds_read_b128 v[182:185], v149
	ds_read_b128 v[192:195], v149 offset:1024
	ds_read_b128 v[196:199], v149 offset:2048
	ds_read_b128 v[200:203], v149 offset:3072
	ds_read_b128 v[204:207], v149 offset:4096
	ds_read_b128 v[208:211], v149 offset:5120
	ds_read_b128 v[212:215], v149 offset:6144
	ds_read_b128 v[216:219], v149 offset:7168
	global_load_lds_dwordx4 v[186:187], off
	v_lshl_add_u64 v[186:187], s[22:23], 0, v[138:139]
	s_add_i32 m0, s21, 0xe000
	s_nop 0
	global_load_lds_dwordx4 v[186:187], off
	s_nop 1
	v_add_f32_e32 v64, 1.0, v70
	v_rcp_f32_e32 v64, v64
	v_add_f32_e32 v65, 1.0, v71
	v_rcp_f32_e32 v65, v65
	v_add_u32_e32 v66, 0x80, v228
	v_mul_f32_e32 v60, v60, v64
	v_mul_f32_e32 v52, v60, v52
	v_mul_f32_e32 v60, v61, v65
	v_mul_f32_e32 v61, 0xbfb8aa3b, v62
	v_exp_f32_e32 v61, v61
	v_mul_f32_e32 v64, 0xbfb8aa3b, v63
	v_exp_f32_e32 v64, v64
	v_mul_f32_e32 v53, v60, v53
	v_add_f32_e32 v60, 1.0, v61
	v_rcp_f32_e32 v60, v60
	v_add_f32_e32 v61, 1.0, v64
	v_mul_f32_e32 v64, 0xbfb8aa3b, v56
	v_rcp_f32_e32 v61, v61
	v_exp_f32_e32 v64, v64
	v_mul_f32_e32 v60, v62, v60
	v_mul_f32_e32 v54, v60, v54
	v_mul_f32_e32 v60, v63, v61
	v_add_f32_e32 v61, 1.0, v64
	v_rcp_f32_e32 v61, v61
	v_mul_f32_e32 v62, 0xbfb8aa3b, v57
	v_exp_f32_e32 v62, v62
	v_mul_f32_e32 v55, v60, v55
	v_mul_f32_e32 v56, v56, v61
	v_mul_f32_e32 v56, v56, v48
	v_add_f32_e32 v48, 1.0, v62
	v_mul_f32_e32 v60, 0xbfb8aa3b, v58
	v_rcp_f32_e32 v48, v48
	v_exp_f32_e32 v60, v60
	v_mul_f32_e32 v61, 0xbfb8aa3b, v59
	v_exp_f32_e32 v61, v61
	v_mul_f32_e32 v48, v57, v48
	v_add_f32_e32 v57, 1.0, v60
	v_rcp_f32_e32 v57, v57
	v_add_f32_e32 v60, 1.0, v61
	v_rcp_f32_e32 v60, v60
	v_mul_f32_e32 v61, v48, v49
	v_mul_f32_e32 v48, v58, v57
	v_mul_f32_e32 v57, v48, v50
	v_mul_f32_e32 v48, v59, v60
	v_mul_f32_e32 v51, v48, v51
	v_cvt_pk_bf16_f32 v48, v52, v53
	v_cvt_pk_bf16_f32 v49, v54, v55
	v_mul_f32_e32 v54, 0xbfb8aa3b, v44
	v_exp_f32_e32 v54, v54
	v_mul_f32_e32 v55, 0xbfb8aa3b, v45
	v_exp_f32_e32 v55, v55
	v_mad_i64_i32 v[52:53], s[100:101], v66, s48, v[112:113]
	v_lshl_add_u64 v[52:53], v[52:53], 0, v[114:115]
	v_cvt_pk_bf16_f32 v50, v56, v61
	v_cvt_pk_bf16_f32 v51, v57, v51
	global_store_dwordx4 v[52:53], v[48:51], off nt
	s_nop 1
	v_add_f32_e32 v48, 1.0, v54
	v_rcp_f32_e32 v48, v48
	v_add_f32_e32 v49, 1.0, v55
	v_rcp_f32_e32 v49, v49
	v_add_u32_e32 v50, 0x90, v228
	v_mul_f32_e32 v44, v44, v48
	v_mul_f32_e32 v36, v44, v36
	v_mul_f32_e32 v44, v45, v49
	v_mul_f32_e32 v45, 0xbfb8aa3b, v46
	v_exp_f32_e32 v45, v45
	v_mul_f32_e32 v48, 0xbfb8aa3b, v47
	v_exp_f32_e32 v48, v48
	v_mul_f32_e32 v37, v44, v37
	v_add_f32_e32 v44, 1.0, v45
	v_rcp_f32_e32 v44, v44
	v_add_f32_e32 v45, 1.0, v48
	v_mul_f32_e32 v48, 0xbfb8aa3b, v40
	v_rcp_f32_e32 v45, v45
	v_exp_f32_e32 v48, v48
	v_mul_f32_e32 v44, v46, v44
	v_mul_f32_e32 v38, v44, v38
	v_mul_f32_e32 v44, v47, v45
	v_add_f32_e32 v45, 1.0, v48
	v_rcp_f32_e32 v45, v45
	v_mul_f32_e32 v46, 0xbfb8aa3b, v41
	v_exp_f32_e32 v46, v46
	v_mul_f32_e32 v39, v44, v39
	v_mul_f32_e32 v40, v40, v45
	v_mul_f32_e32 v40, v40, v32
	v_add_f32_e32 v32, 1.0, v46
	v_mul_f32_e32 v44, 0xbfb8aa3b, v42
	v_rcp_f32_e32 v32, v32
	v_exp_f32_e32 v44, v44
	v_mul_f32_e32 v45, 0xbfb8aa3b, v43
	v_exp_f32_e32 v45, v45
	v_mul_f32_e32 v32, v41, v32
	v_add_f32_e32 v41, 1.0, v44
	v_rcp_f32_e32 v41, v41
	v_add_f32_e32 v44, 1.0, v45
	v_rcp_f32_e32 v44, v44
	v_mul_f32_e32 v45, v32, v33
	v_mul_f32_e32 v32, v42, v41
	v_mul_f32_e32 v41, v32, v34
	v_mul_f32_e32 v32, v43, v44
	v_mul_f32_e32 v35, v32, v35
	v_cvt_pk_bf16_f32 v32, v36, v37
	v_cvt_pk_bf16_f32 v33, v38, v39
	v_mul_f32_e32 v38, 0xbfb8aa3b, v28
	v_exp_f32_e32 v38, v38
	v_mul_f32_e32 v39, 0xbfb8aa3b, v29
	v_exp_f32_e32 v39, v39
	v_mad_i64_i32 v[36:37], s[100:101], v50, s48, v[112:113]
	v_lshl_add_u64 v[36:37], v[36:37], 0, v[114:115]
	v_cvt_pk_bf16_f32 v34, v40, v45
	v_cvt_pk_bf16_f32 v35, v41, v35
	global_store_dwordx4 v[36:37], v[32:35], off nt
	s_nop 1
	v_add_f32_e32 v32, 1.0, v38
	v_rcp_f32_e32 v32, v32
	v_add_f32_e32 v33, 1.0, v39
	v_rcp_f32_e32 v33, v33
	v_add_u32_e32 v34, 0xa0, v228
	v_mul_f32_e32 v28, v28, v32
	v_mul_f32_e32 v20, v28, v20
	v_mul_f32_e32 v28, v29, v33
	v_mul_f32_e32 v29, 0xbfb8aa3b, v30
	v_exp_f32_e32 v29, v29
	v_mul_f32_e32 v32, 0xbfb8aa3b, v31
	v_exp_f32_e32 v32, v32
	v_mul_f32_e32 v21, v28, v21
	v_add_f32_e32 v28, 1.0, v29
	v_rcp_f32_e32 v28, v28
	v_add_f32_e32 v29, 1.0, v32
	v_mul_f32_e32 v32, 0xbfb8aa3b, v24
; #define PG8_STAGE(bufoff, gbase, voff) do { _Pragma("unroll") for (int _i = 0; _i < 2; ++_i) \
;         __builtin_amdgcn_global_load_lds((const unsigned*)((const char*)(gbase) + (voff)[_i]), (PG8_LAS unsigned*)(lds + (bufoff) + ldsw + _i * 8192), 16, 0, 0); } while (0)
; #define PG8_LDA(dst, b, h) do { _Pragma("unroll") for (int m = 0; m < 4; ++m) _Pragma("unroll") for (int k = 0; k < 2; ++k) dst[m][k] = *(const PG8_LAS bf16x8*)(lds + PG8_SA(b, h) + aoff + m * 2048 + k * 1024); } while (0)
; #define PG8_LDB(dst, b, h) do { _Pragma("unroll") for (int n = 0; n < 2; ++n) _Pragma("unroll") for (int k = 0; k < 2; ++k) dst[n][k] = *(const PG8_LAS bf16x8*)(lds + PG8_SB(b, h) + boff + n * 2048 + k * 1024); } while (0)
; #define PG8_WAIT_V(n) asm volatile("s_waitcnt vmcnt(" #n ")" ::: "memory")
; #define PG8_WAIT_L(n) asm volatile("s_waitcnt lgkmcnt(" #n ")" ::: "memory")
; #define PG8_BAR __builtin_amdgcn_s_barrier()
; #define PG8_SCHED __builtin_amdgcn_sched_barrier(0)
; __device__ __forceinline__ float silu_f(float x) { return x * sigmoid_f(x); }
; template <class Epi, class Sched, bool ALIGN_EPI = false, bool SP2 = false>
; __device__ __forceinline__ void gemm_phase(PG8_LAS unsigned char* lds, const Gemm g, const Sched& S, const Epi& E) {
;     ...
;             PG8_LDB(B0, 0, 0); PG8_LDB(B1, 0, 1); PG8_SCHED; PG8_LDA(At, 0, 0); PG8_STAGE(PG8_SA(1, 1), a1 + hstep, voffA);
;             PG8_WAIT_V(8); PG8_WAIT_L(0); PG8_BAR; PG8_MMA(0, 0, At, B0); PG8_MMA(0, 1, At, B1); PG8_BAR; PG8_SCHED;
;             PG8_LDA(At, 0, 1); PG8_STAGE(PG8_SB(0, 0), b2, voffB); PG8_STAGE(PG8_SB(0, 1), b2 + hstep, voffB); PG8_STAGE(PG8_SA(0, 0), a2, voffA);
;     __device__ __forceinline__ void operator()(const f32x4 (&acc)[2][2][4][2], const pg8::Unit& u, int wr, int wc, int fr, int fq) const {
;     ...
;                 const int row = row0 + ai * 128 + m * 16;
;                 const float rs = sumsq ? rsqrtf(sumsq[row] * (1.f / 1024.f) + EPS) : 1.f;
;                 float o[8];
; #pragma unroll
;                 for (int n = 0; n < 2; ++n)
; #pragma unroll
;                     for (int e = 0; e < 4; ++e) { const float g = acc[ai][0][m][n][e] * rs, up = acc[ai][1][m][n][e] * rs; o[4 * n + e] = silu_f(g) * up; }
;                 u32x4 w; w.x = pk2(o[0], o[1]); w.y = pk2(o[2], o[3]); w.z = pk2(o[4], o[5]); w.w = pk2(o[6], o[7]);
;                 *(u32x4*)(H + (size_t)row * DFF + col) = w;
	v_rcp_f32_e32 v29, v29
	v_exp_f32_e32 v32, v32
	v_mul_f32_e32 v28, v30, v28
	v_mul_f32_e32 v22, v28, v22
	v_mul_f32_e32 v28, v31, v29
	v_add_f32_e32 v29, 1.0, v32
	v_rcp_f32_e32 v29, v29
	v_mul_f32_e32 v30, 0xbfb8aa3b, v25
	v_exp_f32_e32 v30, v30
	v_mul_f32_e32 v23, v28, v23
	v_mul_f32_e32 v24, v24, v29
	v_mul_f32_e32 v24, v24, v16
	v_add_f32_e32 v16, 1.0, v30
	v_mul_f32_e32 v28, 0xbfb8aa3b, v26
	v_rcp_f32_e32 v16, v16
	v_exp_f32_e32 v28, v28
	v_mul_f32_e32 v29, 0xbfb8aa3b, v27
	v_exp_f32_e32 v29, v29
	v_mul_f32_e32 v16, v25, v16
	v_add_f32_e32 v25, 1.0, v28
	v_rcp_f32_e32 v25, v25
	v_add_f32_e32 v28, 1.0, v29
	v_rcp_f32_e32 v28, v28
	v_mul_f32_e32 v29, v16, v17
	v_mul_f32_e32 v16, v26, v25
	v_mul_f32_e32 v25, v16, v18
	v_mul_f32_e32 v16, v27, v28
	v_mul_f32_e32 v19, v16, v19
	v_cvt_pk_bf16_f32 v16, v20, v21
	v_cvt_pk_bf16_f32 v17, v22, v23
	v_mul_f32_e32 v22, 0xbfb8aa3b, v12
	v_exp_f32_e32 v22, v22
	v_mul_f32_e32 v23, 0xbfb8aa3b, v13
	v_exp_f32_e32 v23, v23
	v_mad_i64_i32 v[20:21], s[100:101], v34, s48, v[112:113]
	v_lshl_add_u64 v[20:21], v[20:21], 0, v[114:115]
	v_cvt_pk_bf16_f32 v18, v24, v29
	v_cvt_pk_bf16_f32 v19, v25, v19
	global_store_dwordx4 v[20:21], v[16:19], off nt
	s_nop 1
	v_add_f32_e32 v16, 1.0, v22
	v_rcp_f32_e32 v16, v16
	v_add_f32_e32 v17, 1.0, v23
	v_rcp_f32_e32 v17, v17
	v_add_u32_e32 v18, 0xb0, v228
	v_mul_f32_e32 v12, v12, v16
	v_mul_f32_e32 v4, v12, v4
	v_mul_f32_e32 v12, v13, v17
	v_mul_f32_e32 v13, 0xbfb8aa3b, v14
	v_exp_f32_e32 v13, v13
	v_mul_f32_e32 v16, 0xbfb8aa3b, v15
	v_exp_f32_e32 v16, v16
	v_mul_f32_e32 v5, v12, v5
	v_add_f32_e32 v12, 1.0, v13
	v_rcp_f32_e32 v12, v12
	v_add_f32_e32 v13, 1.0, v16
	v_mul_f32_e32 v16, 0xbfb8aa3b, v8
	v_rcp_f32_e32 v13, v13
	v_exp_f32_e32 v16, v16
	v_mul_f32_e32 v12, v14, v12
	v_mul_f32_e32 v6, v12, v6
	v_mul_f32_e32 v12, v15, v13
	v_add_f32_e32 v13, 1.0, v16
	v_rcp_f32_e32 v13, v13
	v_mul_f32_e32 v14, 0xbfb8aa3b, v9
	v_exp_f32_e32 v14, v14
	v_mul_f32_e32 v7, v12, v7
	v_mul_f32_e32 v8, v8, v13
	v_mul_f32_e32 v8, v8, v0
	v_add_f32_e32 v0, 1.0, v14
	v_mul_f32_e32 v12, 0xbfb8aa3b, v10
	v_rcp_f32_e32 v0, v0
	v_exp_f32_e32 v12, v12
	v_mul_f32_e32 v13, 0xbfb8aa3b, v11
	v_exp_f32_e32 v13, v13
	v_mul_f32_e32 v0, v9, v0
	v_add_f32_e32 v9, 1.0, v12
	v_rcp_f32_e32 v9, v9
	v_add_f32_e32 v12, 1.0, v13
	v_rcp_f32_e32 v12, v12
	v_mul_f32_e32 v13, v0, v1
	v_mul_f32_e32 v0, v10, v9
	v_mul_f32_e32 v9, v0, v2
	v_mul_f32_e32 v0, v11, v12
	v_mul_f32_e32 v3, v0, v3
	v_cvt_pk_bf16_f32 v0, v4, v5
	v_mad_i64_i32 v[4:5], s[100:101], v18, s48, v[112:113]
	v_lshl_add_u64 v[4:5], v[4:5], 0, v[114:115]
	v_cvt_pk_bf16_f32 v1, v6, v7
	v_cvt_pk_bf16_f32 v2, v8, v13
	v_cvt_pk_bf16_f32 v3, v9, v3
	global_store_dwordx4 v[4:5], v[0:3], off nt
	s_waitcnt vmcnt(16)
	s_waitcnt lgkmcnt(0)
	s_barrier
	s_setprio 1
	v_mfma_f32_16x16x32_bf16 v[124:127], v[150:153], v[182:185], 0
	v_mfma_f32_16x16x32_bf16 v[120:123], v[158:161], v[182:185], 0
	v_mfma_f32_16x16x32_bf16 v[108:111], v[150:153], v[196:199], 0
	v_mfma_f32_16x16x32_bf16 v[104:107], v[158:161], v[196:199], 0
	v_mfma_f32_16x16x32_bf16 v[92:95], v[150:153], v[204:207], 0
	v_mfma_f32_16x16x32_bf16 v[88:91], v[158:161], v[204:207], 0
	v_mfma_f32_16x16x32_bf16 v[76:79], v[150:153], v[212:215], 0
	v_mfma_f32_16x16x32_bf16 v[72:75], v[158:161], v[212:215], 0
	v_mfma_f32_16x16x32_bf16 v[124:127], v[154:157], v[192:195], v[124:127]
	v_mfma_f32_16x16x32_bf16 v[120:123], v[162:165], v[192:195], v[120:123]
	v_mfma_f32_16x16x32_bf16 v[108:111], v[154:157], v[200:203], v[108:111]
	v_mfma_f32_16x16x32_bf16 v[104:107], v[162:165], v[200:203], v[104:107]
	v_mfma_f32_16x16x32_bf16 v[92:95], v[154:157], v[208:211], v[92:95]
	v_mfma_f32_16x16x32_bf16 v[88:91], v[162:165], v[208:211], v[88:91]
	v_mfma_f32_16x16x32_bf16 v[76:79], v[154:157], v[216:219], v[76:79]
	v_mfma_f32_16x16x32_bf16 v[72:75], v[162:165], v[216:219], v[72:75]
	v_mfma_f32_16x16x32_bf16 v[116:119], v[166:169], v[182:185], 0
	v_mfma_f32_16x16x32_bf16 v[112:115], v[174:177], v[182:185], 0
	v_mfma_f32_16x16x32_bf16 v[100:103], v[166:169], v[196:199], 0
	v_mfma_f32_16x16x32_bf16 v[96:99], v[174:177], v[196:199], 0
	v_mfma_f32_16x16x32_bf16 v[84:87], v[166:169], v[204:207], 0
	v_mfma_f32_16x16x32_bf16 v[80:83], v[174:177], v[204:207], 0
	v_mfma_f32_16x16x32_bf16 v[68:71], v[166:169], v[212:215], 0
	v_mfma_f32_16x16x32_bf16 v[64:67], v[174:177], v[212:215], 0
	v_mfma_f32_16x16x32_bf16 v[116:119], v[170:173], v[192:195], v[116:119]
	v_mfma_f32_16x16x32_bf16 v[112:115], v[178:181], v[192:195], v[112:115]
	v_mfma_f32_16x16x32_bf16 v[100:103], v[170:173], v[200:203], v[100:103]
	v_mfma_f32_16x16x32_bf16 v[96:99], v[178:181], v[200:203], v[96:99]
	v_mfma_f32_16x16x32_bf16 v[84:87], v[170:173], v[208:211], v[84:87]
	v_mfma_f32_16x16x32_bf16 v[80:83], v[178:181], v[208:211], v[80:83]
	v_mfma_f32_16x16x32_bf16 v[68:71], v[170:173], v[216:219], v[68:71]
	v_mfma_f32_16x16x32_bf16 v[64:67], v[178:181], v[216:219], v[64:67]
	s_setprio 0
	s_barrier
	s_add_i32 s55, s46, s35
	v_lshl_add_u64 v[186:187], s[24:25], 0, v[132:133]
	s_mov_b32 m0, s55
	ds_read_b128 v[182:185], v149 offset:16384
	ds_read_b128 v[192:195], v149 offset:17408
	ds_read_b128 v[196:199], v149 offset:18432
	ds_read_b128 v[200:203], v149 offset:19456
	ds_read_b128 v[204:207], v149 offset:20480
	ds_read_b128 v[208:211], v149 offset:21504
	ds_read_b128 v[212:215], v149 offset:22528
	ds_read_b128 v[216:219], v149 offset:23552
	global_load_lds_dwordx4 v[186:187], off
	s_add_i32 m0, s55, 0x2000
	s_add_u32 s56, s24, 0x40000
	v_lshl_add_u64 v[220:221], s[24:25], 0, v[128:129]
	s_addc_u32 s57, s25, 0
	s_add_i32 s55, s47, s35
	global_load_lds_dwordx4 v[220:221], off
	v_lshl_add_u64 v[222:223], s[56:57], 0, v[132:133]
	s_mov_b32 m0, s55
	v_lshl_add_u64 v[224:225], s[30:31], 0, v[130:131]
	global_load_lds_dwordx4 v[222:223], off
	v_lshl_add_u64 v[222:223], s[56:57], 0, v[128:129]
	s_add_i32 m0, s55, 0x2000
	s_nop 0
	global_load_lds_dwordx4 v[222:223], off
	v_lshl_add_u64 v[222:223], s[30:31], 0, v[134:135]
	s_mov_b32 m0, s21
	s_nop 0
	global_load_lds_dwordx4 v[222:223], off
	s_mov_b32 m0, s38
	s_nop 0
	global_load_lds_dwordx4 v[224:225], off
	s_waitcnt vmcnt(16)
	s_waitcnt lgkmcnt(0)
	s_barrier
; #define PG8_STAGE(bufoff, gbase, voff) do { _Pragma("unroll") for (int _i = 0; _i < 2; ++_i) \
;         __builtin_amdgcn_global_load_lds((const unsigned*)((const char*)(gbase) + (voff)[_i]), (PG8_LAS unsigned*)(lds + (bufoff) + ldsw + _i * 8192), 16, 0, 0); } while (0)
; #define PG8_LDA(dst, b, h) do { _Pragma("unroll") for (int m = 0; m < 4; ++m) _Pragma("unroll") for (int k = 0; k < 2; ++k) dst[m][k] = *(const PG8_LAS bf16x8*)(lds + PG8_SA(b, h) + aoff + m * 2048 + k * 1024); } while (0)
; #define PG8_LDB(dst, b, h) do { _Pragma("unroll") for (int n = 0; n < 2; ++n) _Pragma("unroll") for (int k = 0; k < 2; ++k) dst[n][k] = *(const PG8_LAS bf16x8*)(lds + PG8_SB(b, h) + boff + n * 2048 + k * 1024); } while (0)
; #define PG8_MMA(ai, bj, At, Bt) do { __builtin_amdgcn_s_setprio(1); _Pragma("unroll") for (int m = 0; m < 4; ++m) _Pragma("unroll") for (int n = 0; n < 2; ++n) _Pragma("unroll") for (int k = 0; k < 2; ++k) \
;         acc[ai][bj][m][n] = __builtin_amdgcn_mfma_f32_16x16x32_bf16(Bt[n][k], At[m][k], acc[ai][bj][m][n], 0, 0, 0); __builtin_amdgcn_s_setprio(0); } while (0)
; #define PG8_WAIT_V(n) asm volatile("s_waitcnt vmcnt(" #n ")" ::: "memory")
; #define PG8_WAIT_L(n) asm volatile("s_waitcnt lgkmcnt(" #n ")" ::: "memory")
; #define PG8_BAR __builtin_amdgcn_s_barrier()
; #define PG8_SCHED __builtin_amdgcn_sched_barrier(0)
; template <class Epi, class Sched, bool ALIGN_EPI = false, bool SP2 = false>
; __device__ __forceinline__ void gemm_phase(PG8_LAS unsigned char* lds, const Gemm g, const Sched& S, const Epi& E) {
;     ...
;             PG8_WAIT_V(8); PG8_WAIT_L(0); PG8_BAR; PG8_MMA(0, 0, At, B0); PG8_MMA(0, 1, At, B1); PG8_BAR; PG8_SCHED;
;             PG8_LDA(At, 0, 1); PG8_STAGE(PG8_SB(0, 0), b2, voffB); PG8_STAGE(PG8_SB(0, 1), b2 + hstep, voffB); PG8_STAGE(PG8_SA(0, 0), a2, voffA);
;             PG8_WAIT_V(8); PG8_WAIT_L(0); PG8_BAR; PG8_MMA(1, 0, At, B0); PG8_MMA(1, 1, At, B1); PG8_BAR; PG8_SCHED;
;             PG8_LDB(B0, 1, 0); PG8_LDB(B1, 1, 1); PG8_SCHED; PG8_LDA(At, 1, 0); PG8_STAGE(PG8_SA(0, 1), a2 + hstep, voffA);
	s_setprio 1
	v_mfma_f32_16x16x32_bf16 v[60:63], v[150:153], v[182:185], 0
	v_mfma_f32_16x16x32_bf16 v[56:59], v[158:161], v[182:185], 0
	v_mfma_f32_16x16x32_bf16 v[44:47], v[150:153], v[196:199], 0
	v_mfma_f32_16x16x32_bf16 v[40:43], v[158:161], v[196:199], 0
	v_mfma_f32_16x16x32_bf16 v[28:31], v[150:153], v[204:207], 0
	v_mfma_f32_16x16x32_bf16 v[24:27], v[158:161], v[204:207], 0
	v_mfma_f32_16x16x32_bf16 v[12:15], v[150:153], v[212:215], 0
	v_mfma_f32_16x16x32_bf16 v[8:11], v[158:161], v[212:215], 0
	v_mfma_f32_16x16x32_bf16 v[60:63], v[154:157], v[192:195], v[60:63]
	v_mfma_f32_16x16x32_bf16 v[56:59], v[162:165], v[192:195], v[56:59]
	v_mfma_f32_16x16x32_bf16 v[44:47], v[154:157], v[200:203], v[44:47]
	v_mfma_f32_16x16x32_bf16 v[40:43], v[162:165], v[200:203], v[40:43]
	v_mfma_f32_16x16x32_bf16 v[28:31], v[154:157], v[208:211], v[28:31]
	v_mfma_f32_16x16x32_bf16 v[24:27], v[162:165], v[208:211], v[24:27]
	v_mfma_f32_16x16x32_bf16 v[12:15], v[154:157], v[216:219], v[12:15]
	v_mfma_f32_16x16x32_bf16 v[8:11], v[162:165], v[216:219], v[8:11]
	v_mfma_f32_16x16x32_bf16 v[52:55], v[166:169], v[182:185], 0
	v_mfma_f32_16x16x32_bf16 v[48:51], v[174:177], v[182:185], 0
	v_mfma_f32_16x16x32_bf16 v[36:39], v[166:169], v[196:199], 0
	v_mfma_f32_16x16x32_bf16 v[32:35], v[174:177], v[196:199], 0
	v_mfma_f32_16x16x32_bf16 v[20:23], v[166:169], v[204:207], 0
	v_mfma_f32_16x16x32_bf16 v[16:19], v[174:177], v[204:207], 0
	v_mfma_f32_16x16x32_bf16 v[4:7], v[166:169], v[212:215], 0
	v_mfma_f32_16x16x32_bf16 v[0:3], v[174:177], v[212:215], 0
	v_mfma_f32_16x16x32_bf16 v[52:55], v[170:173], v[192:195], v[52:55]
	v_mfma_f32_16x16x32_bf16 v[48:51], v[178:181], v[192:195], v[48:51]
	v_mfma_f32_16x16x32_bf16 v[36:39], v[170:173], v[200:203], v[36:39]
	v_mfma_f32_16x16x32_bf16 v[32:35], v[178:181], v[200:203], v[32:35]
	v_mfma_f32_16x16x32_bf16 v[20:23], v[170:173], v[208:211], v[20:23]
	v_mfma_f32_16x16x32_bf16 v[16:19], v[178:181], v[208:211], v[16:19]
	v_mfma_f32_16x16x32_bf16 v[4:7], v[170:173], v[216:219], v[4:7]
	v_mfma_f32_16x16x32_bf16 v[0:3], v[178:181], v[216:219], v[0:3]
	s_setprio 0
	s_barrier
	s_add_i32 s55, 0, 0x18000
	s_add_i32 s56, 0, 0x1c000
	v_add_u32_e32 v162, s55, v145
	v_add_u32_e32 v178, s56, v145
	ds_read_b128 v[150:153], v162
	ds_read_b128 v[154:157], v162 offset:1024
	ds_read_b128 v[158:161], v162 offset:2048
	ds_read_b128 v[162:165], v162 offset:3072
	ds_read_b128 v[166:169], v178
	ds_read_b128 v[170:173], v178 offset:1024
	ds_read_b128 v[174:177], v178 offset:2048
	ds_read_b128 v[178:181], v178 offset:3072
	s_add_u32 s30, s30, 0x40000
	s_addc_u32 s31, s31, 0
	s_mov_b32 m0, s39
	v_lshl_add_u64 v[226:227], s[30:31], 0, v[134:135]
	ds_read_b128 v[182:185], v149 offset:32768
	ds_read_b128 v[192:195], v149 offset:33792
	ds_read_b128 v[196:199], v149 offset:34816
	ds_read_b128 v[200:203], v149 offset:35840
	ds_read_b128 v[204:207], v149 offset:36864
	ds_read_b128 v[208:211], v149 offset:37888
	ds_read_b128 v[212:215], v149 offset:38912
	ds_read_b128 v[216:219], v149 offset:39936
	global_load_lds_dwordx4 v[226:227], off
	v_lshl_add_u64 v[226:227], s[30:31], 0, v[130:131]
	s_mov_b32 m0, s40
	s_nop 0
	global_load_lds_dwordx4 v[226:227], off
	s_waitcnt vmcnt(8)
	s_waitcnt lgkmcnt(0)
	s_barrier
	s_setprio 1
	v_mfma_f32_16x16x32_bf16 v[124:127], v[150:153], v[182:185], v[124:127]
	v_mfma_f32_16x16x32_bf16 v[120:123], v[158:161], v[182:185], v[120:123]
	v_mfma_f32_16x16x32_bf16 v[108:111], v[150:153], v[196:199], v[108:111]
	v_mfma_f32_16x16x32_bf16 v[104:107], v[158:161], v[196:199], v[104:107]
	v_mfma_f32_16x16x32_bf16 v[92:95], v[150:153], v[204:207], v[92:95]
	v_mfma_f32_16x16x32_bf16 v[88:91], v[158:161], v[204:207], v[88:91]
	v_mfma_f32_16x16x32_bf16 v[76:79], v[150:153], v[212:215], v[76:79]
	v_mfma_f32_16x16x32_bf16 v[72:75], v[158:161], v[212:215], v[72:75]
	v_mfma_f32_16x16x32_bf16 v[124:127], v[154:157], v[192:195], v[124:127]
	v_mfma_f32_16x16x32_bf16 v[120:123], v[162:165], v[192:195], v[120:123]
	v_mfma_f32_16x16x32_bf16 v[108:111], v[154:157], v[200:203], v[108:111]
	v_mfma_f32_16x16x32_bf16 v[104:107], v[162:165], v[200:203], v[104:107]
	v_mfma_f32_16x16x32_bf16 v[92:95], v[154:157], v[208:211], v[92:95]
	v_mfma_f32_16x16x32_bf16 v[88:91], v[162:165], v[208:211], v[88:91]
	v_mfma_f32_16x16x32_bf16 v[76:79], v[154:157], v[216:219], v[76:79]
	v_mfma_f32_16x16x32_bf16 v[72:75], v[162:165], v[216:219], v[72:75]
	v_mfma_f32_16x16x32_bf16 v[116:119], v[166:169], v[182:185], v[116:119]
	v_mfma_f32_16x16x32_bf16 v[112:115], v[174:177], v[182:185], v[112:115]
	v_mfma_f32_16x16x32_bf16 v[100:103], v[166:169], v[196:199], v[100:103]
	v_mfma_f32_16x16x32_bf16 v[96:99], v[174:177], v[196:199], v[96:99]
	v_mfma_f32_16x16x32_bf16 v[84:87], v[166:169], v[204:207], v[84:87]
	v_mfma_f32_16x16x32_bf16 v[80:83], v[174:177], v[204:207], v[80:83]
	v_mfma_f32_16x16x32_bf16 v[68:71], v[166:169], v[212:215], v[68:71]
	v_mfma_f32_16x16x32_bf16 v[64:67], v[174:177], v[212:215], v[64:67]
	v_mfma_f32_16x16x32_bf16 v[116:119], v[170:173], v[192:195], v[116:119]
	v_mfma_f32_16x16x32_bf16 v[112:115], v[178:181], v[192:195], v[112:115]
	v_mfma_f32_16x16x32_bf16 v[100:103], v[170:173], v[200:203], v[100:103]
	v_mfma_f32_16x16x32_bf16 v[96:99], v[178:181], v[200:203], v[96:99]
	v_mfma_f32_16x16x32_bf16 v[84:87], v[170:173], v[208:211], v[84:87]
	v_mfma_f32_16x16x32_bf16 v[80:83], v[178:181], v[208:211], v[80:83]
	v_mfma_f32_16x16x32_bf16 v[68:71], v[170:173], v[216:219], v[68:71]
	v_mfma_f32_16x16x32_bf16 v[64:67], v[178:181], v[216:219], v[64:67]
	s_setprio 0
	s_barrier
; #define PG8_STAGE(bufoff, gbase, voff) do { _Pragma("unroll") for (int _i = 0; _i < 2; ++_i) \
;         __builtin_amdgcn_global_load_lds((const unsigned*)((const char*)(gbase) + (voff)[_i]), (PG8_LAS unsigned*)(lds + (bufoff) + ldsw + _i * 8192), 16, 0, 0); } while (0)
; #define PG8_LDA(dst, b, h) do { _Pragma("unroll") for (int m = 0; m < 4; ++m) _Pragma("unroll") for (int k = 0; k < 2; ++k) dst[m][k] = *(const PG8_LAS bf16x8*)(lds + PG8_SA(b, h) + aoff + m * 2048 + k * 1024); } while (0)
; #define PG8_LDB(dst, b, h) do { _Pragma("unroll") for (int n = 0; n < 2; ++n) _Pragma("unroll") for (int k = 0; k < 2; ++k) dst[n][k] = *(const PG8_LAS bf16x8*)(lds + PG8_SB(b, h) + boff + n * 2048 + k * 1024); } while (0)
; #define PG8_MMA(ai, bj, At, Bt) do { __builtin_amdgcn_s_setprio(1); _Pragma("unroll") for (int m = 0; m < 4; ++m) _Pragma("unroll") for (int n = 0; n < 2; ++n) _Pragma("unroll") for (int k = 0; k < 2; ++k) \
;         acc[ai][bj][m][n] = __builtin_amdgcn_mfma_f32_16x16x32_bf16(Bt[n][k], At[m][k], acc[ai][bj][m][n], 0, 0, 0); __builtin_amdgcn_s_setprio(0); } while (0)
; #define PG8_WAIT_V(n) asm volatile("s_waitcnt vmcnt(" #n ")" ::: "memory")
; #define PG8_WAIT_L(n) asm volatile("s_waitcnt lgkmcnt(" #n ")" ::: "memory")
; #define PG8_BAR __builtin_amdgcn_s_barrier()
; #define PG8_SCHED __builtin_amdgcn_sched_barrier(0)
; template <class Epi, class Sched, bool ALIGN_EPI = false, bool SP2 = false>
; __device__ __forceinline__ void gemm_phase(PG8_LAS unsigned char* lds, const Gemm g, const Sched& S, const Epi& E) {
;     ...
;             PG8_LDB(B0, 1, 0); PG8_LDB(B1, 1, 1); PG8_SCHED; PG8_LDA(At, 1, 0); PG8_STAGE(PG8_SA(0, 1), a2 + hstep, voffA);
;             PG8_WAIT_V(8); PG8_WAIT_L(0); PG8_BAR; PG8_MMA(0, 0, At, B0); PG8_MMA(0, 1, At, B1); PG8_BAR; PG8_SCHED;
;             PG8_LDA(At, 1, 1); PG8_STAGE(PG8_SB(1, 0), b3, voffB); PG8_STAGE(PG8_SB(1, 1), b3 + hstep, voffB); PG8_STAGE(PG8_SA(1, 0), a3, voffA);
;             PG8_WAIT_V(8); PG8_WAIT_L(0); PG8_BAR; PG8_MMA(1, 0, At, B0); PG8_MMA(1, 1, At, B1); PG8_BAR; PG8_SCHED;
	s_add_i32 s30, s55, s35
	v_lshl_add_u64 v[186:187], v[186:187], 0, s[4:5]
	s_mov_b32 m0, s30
	ds_read_b128 v[182:185], v149 offset:49152
	ds_read_b128 v[192:195], v149 offset:50176
	ds_read_b128 v[196:199], v149 offset:51200
	ds_read_b128 v[200:203], v149 offset:52224
	ds_read_b128 v[204:207], v149 offset:53248
	ds_read_b128 v[208:211], v149 offset:54272
	ds_read_b128 v[212:215], v149 offset:55296
	ds_read_b128 v[216:219], v149 offset:56320
	global_load_lds_dwordx4 v[186:187], off
	s_add_i32 m0, s30, 0x2000
	s_add_u32 s24, s24, 0x40080
	v_lshl_add_u64 v[186:187], v[220:221], 0, s[4:5]
	s_addc_u32 s25, s25, 0
	s_add_i32 s30, s56, s35
	global_load_lds_dwordx4 v[186:187], off
	v_lshl_add_u64 v[186:187], s[24:25], 0, v[132:133]
	s_mov_b32 m0, s30
	s_nop 0
	global_load_lds_dwordx4 v[186:187], off
	v_lshl_add_u64 v[186:187], s[24:25], 0, v[128:129]
	s_add_i32 m0, s30, 0x2000
	s_nop 0
	global_load_lds_dwordx4 v[186:187], off
	v_lshl_add_u64 v[186:187], v[222:223], 0, s[4:5]
	s_mov_b32 m0, s42
	s_nop 0
	global_load_lds_dwordx4 v[186:187], off
	v_lshl_add_u64 v[186:187], v[224:225], 0, s[4:5]
	s_mov_b32 m0, s43
	s_nop 0
	global_load_lds_dwordx4 v[186:187], off
	s_waitcnt vmcnt(8)
	s_waitcnt lgkmcnt(0)
	s_barrier
	s_setprio 1
	v_mfma_f32_16x16x32_bf16 v[60:63], v[150:153], v[182:185], v[60:63]
	v_mfma_f32_16x16x32_bf16 v[56:59], v[158:161], v[182:185], v[56:59]
	v_mfma_f32_16x16x32_bf16 v[44:47], v[150:153], v[196:199], v[44:47]
	v_mfma_f32_16x16x32_bf16 v[40:43], v[158:161], v[196:199], v[40:43]
	v_mfma_f32_16x16x32_bf16 v[28:31], v[150:153], v[204:207], v[28:31]
	v_mfma_f32_16x16x32_bf16 v[24:27], v[158:161], v[204:207], v[24:27]
	v_mfma_f32_16x16x32_bf16 v[12:15], v[150:153], v[212:215], v[12:15]
	v_mfma_f32_16x16x32_bf16 v[8:11], v[158:161], v[212:215], v[8:11]
	v_mfma_f32_16x16x32_bf16 v[60:63], v[154:157], v[192:195], v[60:63]
	v_mfma_f32_16x16x32_bf16 v[56:59], v[162:165], v[192:195], v[56:59]
	v_mfma_f32_16x16x32_bf16 v[44:47], v[154:157], v[200:203], v[44:47]
	v_mfma_f32_16x16x32_bf16 v[40:43], v[162:165], v[200:203], v[40:43]
	v_mfma_f32_16x16x32_bf16 v[28:31], v[154:157], v[208:211], v[28:31]
	v_mfma_f32_16x16x32_bf16 v[24:27], v[162:165], v[208:211], v[24:27]
	v_mfma_f32_16x16x32_bf16 v[12:15], v[154:157], v[216:219], v[12:15]
	v_mfma_f32_16x16x32_bf16 v[8:11], v[162:165], v[216:219], v[8:11]
	v_mfma_f32_16x16x32_bf16 v[52:55], v[166:169], v[182:185], v[52:55]
	v_mfma_f32_16x16x32_bf16 v[48:51], v[174:177], v[182:185], v[48:51]
	v_mfma_f32_16x16x32_bf16 v[36:39], v[166:169], v[196:199], v[36:39]
	v_mfma_f32_16x16x32_bf16 v[32:35], v[174:177], v[196:199], v[32:35]
	v_mfma_f32_16x16x32_bf16 v[20:23], v[166:169], v[204:207], v[20:23]
	v_mfma_f32_16x16x32_bf16 v[16:19], v[174:177], v[204:207], v[16:19]
	v_mfma_f32_16x16x32_bf16 v[4:7], v[166:169], v[212:215], v[4:7]
	v_mfma_f32_16x16x32_bf16 v[0:3], v[174:177], v[212:215], v[0:3]
	v_mfma_f32_16x16x32_bf16 v[52:55], v[170:173], v[192:195], v[52:55]
	v_mfma_f32_16x16x32_bf16 v[48:51], v[178:181], v[192:195], v[48:51]
	v_mfma_f32_16x16x32_bf16 v[36:39], v[170:173], v[200:203], v[36:39]
	v_mfma_f32_16x16x32_bf16 v[32:35], v[178:181], v[200:203], v[32:35]
	v_mfma_f32_16x16x32_bf16 v[20:23], v[170:173], v[208:211], v[20:23]
	v_mfma_f32_16x16x32_bf16 v[16:19], v[178:181], v[208:211], v[16:19]
	v_mfma_f32_16x16x32_bf16 v[4:7], v[170:173], v[216:219], v[4:7]
	v_mfma_f32_16x16x32_bf16 v[0:3], v[178:181], v[216:219], v[0:3]
	s_setprio 0
	s_barrier
	s_add_i32 s54, s54, 2
	s_add_u32 s22, s22, 0x100
	s_addc_u32 s23, s23, 0
	s_add_u32 s52, s52, 0x100
	s_addc_u32 s53, s53, 0
	s_branch .LBB0_192

; __device__ __forceinline__ unsigned pk2(float lo, float hi) { return pg8::cvt_pk_bf16(lo, hi); }
; __device__ __forceinline__ float silu_f(float x) { return x * sigmoid_f(x); }
;     __device__ __forceinline__ void operator()(const f32x4 (&acc)[2][2][4][2], const pg8::Unit& u, int wr, int wc, int fr, int fq) const {
;         const int row0 = u.pm * 256 + wr * 64 + fr, col = u.pn * 128 + wc * 32 + 8 * fq;
; #pragma unroll
;         for (int ai = 0; ai < 2; ++ai)
; #pragma unroll
;             for (int m = 0; m < 4; ++m) {
;                 const int row = row0 + ai * 128 + m * 16;
;                 const float rs = sumsq ? rsqrtf(sumsq[row] * (1.f / 1024.f) + EPS) : 1.f;
;                 float o[8];
; #pragma unroll
;                 for (int n = 0; n < 2; ++n)
; #pragma unroll
;                     for (int e = 0; e < 4; ++e) { const float g = acc[ai][0][m][n][e] * rs, up = acc[ai][1][m][n][e] * rs; o[4 * n + e] = silu_f(g) * up; }
;                 u32x4 w; w.x = pk2(o[0], o[1]); w.y = pk2(o[2], o[3]); w.z = pk2(o[4], o[5]); w.w = pk2(o[6], o[7]);
;                 *(u32x4*)(H + (size_t)row * DFF + col) = w;
.LBB0_195:
	v_mul_f32_e32 v151, 0xbfb8aa3b, v124
	v_exp_f32_e32 v151, v151
	v_mul_f32_e32 v152, 0xbfb8aa3b, v125
	v_exp_f32_e32 v153, v152
	v_readlane_b32 s22, v235, 33
	v_add_f32_e32 v151, 1.0, v151
	v_rcp_f32_e32 v151, v151
	v_add_f32_e32 v153, 1.0, v153
	v_rcp_f32_e32 v154, v153
	v_lshl_or_b32 v152, s49, 7, v146
	v_mul_f32_e32 v124, v124, v151
	v_mul_f32_e32 v116, v124, v116
	v_mul_f32_e32 v124, v125, v154
	v_mul_f32_e32 v125, 0xbfb8aa3b, v126
	v_exp_f32_e32 v125, v125
	v_mul_f32_e32 v151, 0xbfb8aa3b, v127
	v_exp_f32_e32 v151, v151
	v_mul_f32_e32 v117, v124, v117
	v_add_f32_e32 v124, 1.0, v125
	v_rcp_f32_e32 v124, v124
	v_add_f32_e32 v125, 1.0, v151
	v_mul_f32_e32 v151, 0xbfb8aa3b, v120
	v_rcp_f32_e32 v125, v125
	v_exp_f32_e32 v151, v151
	v_mul_f32_e32 v124, v126, v124
	v_mul_f32_e32 v118, v124, v118
	v_mul_f32_e32 v124, v127, v125
	v_add_f32_e32 v125, 1.0, v151
	v_rcp_f32_e32 v125, v125
	v_mul_f32_e32 v126, 0xbfb8aa3b, v121
	v_exp_f32_e32 v126, v126
	v_mul_f32_e32 v119, v124, v119
	v_mul_f32_e32 v120, v120, v125
	v_mul_f32_e32 v112, v120, v112
	v_add_f32_e32 v120, 1.0, v126
	v_mul_f32_e32 v124, 0xbfb8aa3b, v122
	v_rcp_f32_e32 v120, v120
	v_exp_f32_e32 v124, v124
	v_mul_f32_e32 v125, 0xbfb8aa3b, v123
	v_exp_f32_e32 v125, v125
	v_mul_f32_e32 v120, v121, v120
	v_add_f32_e32 v121, 1.0, v124
	v_rcp_f32_e32 v121, v121
	v_add_f32_e32 v124, 1.0, v125
	v_rcp_f32_e32 v124, v124
	v_mul_f32_e32 v113, v120, v113
	v_mul_f32_e32 v120, v122, v121
	v_mul_f32_e32 v122, 0xbfb8aa3b, v108
	v_mul_f32_e32 v114, v120, v114
	v_mul_f32_e32 v120, v123, v124
	v_readlane_b32 s23, v235, 34
	v_exp_f32_e32 v122, v122
	v_mul_f32_e32 v123, 0xbfb8aa3b, v109
	v_lshl_add_u32 v228, s20, 8, v144
	v_ashrrev_i32_e32 v153, 31, v152
	v_mul_f32_e32 v115, v120, v115
	v_cvt_pk_bf16_f32 v116, v116, v117
	v_cvt_pk_bf16_f32 v117, v118, v119
	v_cvt_pk_bf16_f32 v118, v112, v113
	v_mov_b64_e32 v[112:113], s[22:23]
	v_exp_f32_e32 v123, v123
	v_cvt_pk_bf16_f32 v119, v114, v115
	v_mad_i64_i32 v[120:121], s[22:23], v228, s48, v[112:113]
	v_lshlrev_b64 v[114:115], 1, v[152:153]
	v_lshl_add_u64 v[120:121], v[120:121], 0, v[114:115]
	global_store_dwordx4 v[120:121], v[116:119], off nt
	s_andn2_b64 vcc, exec, s[0:1]
	s_mov_b64 s[0:1], -1
	v_add_f32_e32 v116, 1.0, v122
	v_rcp_f32_e32 v116, v116
	v_add_f32_e32 v117, 1.0, v123
	v_rcp_f32_e32 v117, v117
	v_or_b32_e32 v118, 16, v228
	v_mul_f32_e32 v108, v108, v116
	v_mul_f32_e32 v100, v108, v100
	v_mul_f32_e32 v108, v109, v117
	v_mul_f32_e32 v109, 0xbfb8aa3b, v110
	v_exp_f32_e32 v109, v109
	v_mul_f32_e32 v116, 0xbfb8aa3b, v111
	v_exp_f32_e32 v116, v116
	v_mul_f32_e32 v101, v108, v101
	v_add_f32_e32 v108, 1.0, v109
	v_rcp_f32_e32 v108, v108
	v_add_f32_e32 v109, 1.0, v116
	v_mul_f32_e32 v116, 0xbfb8aa3b, v104
	v_rcp_f32_e32 v109, v109
	v_exp_f32_e32 v116, v116
	v_mul_f32_e32 v108, v110, v108
	v_mul_f32_e32 v102, v108, v102
	v_mul_f32_e32 v108, v111, v109
	v_add_f32_e32 v109, 1.0, v116
	v_rcp_f32_e32 v109, v109
	v_mul_f32_e32 v110, 0xbfb8aa3b, v105
	v_exp_f32_e32 v110, v110
	v_mul_f32_e32 v103, v108, v103
	v_mul_f32_e32 v104, v104, v109
	v_mul_f32_e32 v104, v104, v96
	v_add_f32_e32 v96, 1.0, v110
	v_mul_f32_e32 v108, 0xbfb8aa3b, v106
	v_rcp_f32_e32 v96, v96
	v_exp_f32_e32 v108, v108
	v_mul_f32_e32 v109, 0xbfb8aa3b, v107
	v_exp_f32_e32 v109, v109
	v_mul_f32_e32 v96, v105, v96
	v_add_f32_e32 v105, 1.0, v108
	v_rcp_f32_e32 v105, v105
	v_add_f32_e32 v108, 1.0, v109
	v_rcp_f32_e32 v108, v108
	v_mul_f32_e32 v109, v96, v97
	v_mul_f32_e32 v96, v106, v105
	v_mul_f32_e32 v105, v96, v98
	v_mul_f32_e32 v96, v107, v108
	v_mul_f32_e32 v99, v96, v99
	v_cvt_pk_bf16_f32 v96, v100, v101
	v_cvt_pk_bf16_f32 v97, v102, v103
	v_mul_f32_e32 v102, 0xbfb8aa3b, v92
	v_exp_f32_e32 v102, v102
	v_mul_f32_e32 v103, 0xbfb8aa3b, v93
	v_exp_f32_e32 v103, v103
	v_mad_i64_i32 v[100:101], s[22:23], v118, s48, v[112:113]
	v_lshl_add_u64 v[100:101], v[100:101], 0, v[114:115]
	v_cvt_pk_bf16_f32 v98, v104, v109
	v_cvt_pk_bf16_f32 v99, v105, v99
	global_store_dwordx4 v[100:101], v[96:99], off nt
	s_nop 1
	v_add_f32_e32 v96, 1.0, v102
	v_rcp_f32_e32 v96, v96
	v_add_f32_e32 v97, 1.0, v103
	v_rcp_f32_e32 v97, v97
	v_or_b32_e32 v98, 32, v228
	v_mul_f32_e32 v92, v92, v96
	v_mul_f32_e32 v84, v92, v84
	v_mul_f32_e32 v92, v93, v97
	v_mul_f32_e32 v93, 0xbfb8aa3b, v94
	v_exp_f32_e32 v93, v93
	v_mul_f32_e32 v96, 0xbfb8aa3b, v95
	v_exp_f32_e32 v96, v96
	v_mul_f32_e32 v85, v92, v85
	v_add_f32_e32 v92, 1.0, v93
	v_rcp_f32_e32 v92, v92
	v_add_f32_e32 v93, 1.0, v96
	v_mul_f32_e32 v96, 0xbfb8aa3b, v88
	v_rcp_f32_e32 v93, v93
	v_exp_f32_e32 v96, v96
	v_mul_f32_e32 v92, v94, v92
	v_mul_f32_e32 v86, v92, v86
	v_mul_f32_e32 v92, v95, v93
	v_add_f32_e32 v93, 1.0, v96
	v_rcp_f32_e32 v93, v93
	v_mul_f32_e32 v94, 0xbfb8aa3b, v89
	v_exp_f32_e32 v94, v94
	v_mul_f32_e32 v87, v92, v87
	v_mul_f32_e32 v88, v88, v93
	v_mul_f32_e32 v88, v88, v80
	v_add_f32_e32 v80, 1.0, v94
	v_mul_f32_e32 v92, 0xbfb8aa3b, v90
	v_rcp_f32_e32 v80, v80
	v_exp_f32_e32 v92, v92
	v_mul_f32_e32 v93, 0xbfb8aa3b, v91
	v_exp_f32_e32 v93, v93
	v_mul_f32_e32 v80, v89, v80
	v_add_f32_e32 v89, 1.0, v92
	v_rcp_f32_e32 v89, v89
	v_add_f32_e32 v92, 1.0, v93
	v_rcp_f32_e32 v92, v92
	v_mul_f32_e32 v93, v80, v81
	v_mul_f32_e32 v80, v90, v89
	v_mul_f32_e32 v89, v80, v82
	v_mul_f32_e32 v80, v91, v92
	v_mul_f32_e32 v83, v80, v83
	v_cvt_pk_bf16_f32 v80, v84, v85
	v_cvt_pk_bf16_f32 v81, v86, v87
	v_mul_f32_e32 v86, 0xbfb8aa3b, v76
	v_exp_f32_e32 v86, v86
	v_mul_f32_e32 v87, 0xbfb8aa3b, v77
	v_exp_f32_e32 v87, v87
	v_mad_i64_i32 v[84:85], s[22:23], v98, s48, v[112:113]
	v_lshl_add_u64 v[84:85], v[84:85], 0, v[114:115]
	v_cvt_pk_bf16_f32 v82, v88, v93
; __device__ __forceinline__ unsigned pk2(float lo, float hi) { return pg8::cvt_pk_bf16(lo, hi); }
; __device__ __forceinline__ float silu_f(float x) { return x * sigmoid_f(x); }
;     __device__ __forceinline__ void operator()(const f32x4 (&acc)[2][2][4][2], const pg8::Unit& u, int wr, int wc, int fr, int fq) const {
;         const int row0 = u.pm * 256 + wr * 64 + fr, col = u.pn * 128 + wc * 32 + 8 * fq;
; #pragma unroll
;         for (int ai = 0; ai < 2; ++ai)
; #pragma unroll
;             for (int m = 0; m < 4; ++m) {
;                 const int row = row0 + ai * 128 + m * 16;
;                 const float rs = sumsq ? rsqrtf(sumsq[row] * (1.f / 1024.f) + EPS) : 1.f;
;                 float o[8];
; #pragma unroll
;                 for (int n = 0; n < 2; ++n)
; #pragma unroll
;                     for (int e = 0; e < 4; ++e) { const float g = acc[ai][0][m][n][e] * rs, up = acc[ai][1][m][n][e] * rs; o[4 * n + e] = silu_f(g) * up; }
;                 u32x4 w; w.x = pk2(o[0], o[1]); w.y = pk2(o[2], o[3]); w.z = pk2(o[4], o[5]); w.w = pk2(o[6], o[7]);
;                 *(u32x4*)(H + (size_t)row * DFF + col) = w;
	v_cvt_pk_bf16_f32 v83, v89, v83
	global_store_dwordx4 v[84:85], v[80:83], off nt
	s_nop 1
	v_add_f32_e32 v80, 1.0, v86
	v_rcp_f32_e32 v80, v80
	v_add_f32_e32 v81, 1.0, v87
	v_rcp_f32_e32 v81, v81
	v_or_b32_e32 v82, 48, v228
	v_mul_f32_e32 v76, v76, v80
	v_mul_f32_e32 v68, v76, v68
	v_mul_f32_e32 v76, v77, v81
	v_mul_f32_e32 v77, 0xbfb8aa3b, v78
	v_exp_f32_e32 v77, v77
	v_mul_f32_e32 v80, 0xbfb8aa3b, v79
	v_exp_f32_e32 v80, v80
	v_mul_f32_e32 v69, v76, v69
	v_add_f32_e32 v76, 1.0, v77
	v_rcp_f32_e32 v76, v76
	v_add_f32_e32 v77, 1.0, v80
	v_mul_f32_e32 v80, 0xbfb8aa3b, v72
	v_rcp_f32_e32 v77, v77
	v_exp_f32_e32 v80, v80
	v_mul_f32_e32 v76, v78, v76
	v_mul_f32_e32 v70, v76, v70
	v_mul_f32_e32 v76, v79, v77
	v_add_f32_e32 v77, 1.0, v80
	v_rcp_f32_e32 v77, v77
	v_mul_f32_e32 v78, 0xbfb8aa3b, v73
	v_exp_f32_e32 v78, v78
	v_mul_f32_e32 v71, v76, v71
	v_mul_f32_e32 v72, v72, v77
	v_mul_f32_e32 v72, v72, v64
	v_add_f32_e32 v64, 1.0, v78
	v_mul_f32_e32 v76, 0xbfb8aa3b, v74
	v_rcp_f32_e32 v64, v64
	v_exp_f32_e32 v76, v76
	v_mul_f32_e32 v77, 0xbfb8aa3b, v75
	v_exp_f32_e32 v77, v77
	v_mul_f32_e32 v64, v73, v64
	v_add_f32_e32 v73, 1.0, v76
	v_rcp_f32_e32 v73, v73
	v_add_f32_e32 v76, 1.0, v77
	v_rcp_f32_e32 v76, v76
	v_mul_f32_e32 v77, v64, v65
	v_mul_f32_e32 v64, v74, v73
	v_mul_f32_e32 v73, v64, v66
	v_mul_f32_e32 v64, v75, v76
	v_mul_f32_e32 v67, v64, v67
	v_cvt_pk_bf16_f32 v64, v68, v69
	v_cvt_pk_bf16_f32 v65, v70, v71
	v_mul_f32_e32 v70, 0xbfb8aa3b, v60
	v_exp_f32_e32 v70, v70
	v_mul_f32_e32 v71, 0xbfb8aa3b, v61
	v_exp_f32_e32 v71, v71
	v_mad_i64_i32 v[68:69], s[22:23], v82, s48, v[112:113]
	v_lshl_add_u64 v[68:69], v[68:69], 0, v[114:115]
	v_cvt_pk_bf16_f32 v66, v72, v77
	v_cvt_pk_bf16_f32 v67, v73, v67
	global_store_dwordx4 v[68:69], v[64:67], off nt
	s_mov_b32 s98, 1
	s_cbranch_vccnz .LBB0_188
	s_andn2_b64 vcc, exec, s[2:3]
	s_cbranch_vccnz .LBB0_187
	s_barrier
	s_branch .LBB0_187
; __device__ __forceinline__ unsigned pk2(float lo, float hi) { return pg8::cvt_pk_bf16(lo, hi); }
; __device__ __forceinline__ float silu_f(float x) { return x * sigmoid_f(x); }
;     __device__ __forceinline__ void operator()(const f32x4 (&acc)[2][2][4][2], const pg8::Unit& u, int wr, int wc, int fr, int fq) const {
;         const int row0 = u.pm * 256 + wr * 64 + fr, col = u.pn * 128 + wc * 32 + 8 * fq;
; #pragma unroll
;         for (int ai = 0; ai < 2; ++ai)
; #pragma unroll
;             for (int m = 0; m < 4; ++m) {
;                 const int row = row0 + ai * 128 + m * 16;
;                 const float rs = sumsq ? rsqrtf(sumsq[row] * (1.f / 1024.f) + EPS) : 1.f;
;                 float o[8];
; #pragma unroll
;                 for (int n = 0; n < 2; ++n)
; #pragma unroll
;                     for (int e = 0; e < 4; ++e) { const float g = acc[ai][0][m][n][e] * rs, up = acc[ai][1][m][n][e] * rs; o[4 * n + e] = silu_f(g) * up; }
;                 u32x4 w; w.x = pk2(o[0], o[1]); w.y = pk2(o[2], o[3]); w.z = pk2(o[4], o[5]); w.w = pk2(o[6], o[7]);
;                 *(u32x4*)(H + (size_t)row * DFF + col) = w;
.Lp1_tail:
	s_nop 1
	v_add_f32_e32 v64, 1.0, v70
	v_rcp_f32_e32 v64, v64
	v_add_f32_e32 v65, 1.0, v71
	v_rcp_f32_e32 v65, v65
	v_add_u32_e32 v66, 0x80, v228
	v_mul_f32_e32 v60, v60, v64
	v_mul_f32_e32 v52, v60, v52
	v_mul_f32_e32 v60, v61, v65
	v_mul_f32_e32 v61, 0xbfb8aa3b, v62
	v_exp_f32_e32 v61, v61
	v_mul_f32_e32 v64, 0xbfb8aa3b, v63
	v_exp_f32_e32 v64, v64
	v_mul_f32_e32 v53, v60, v53
	v_add_f32_e32 v60, 1.0, v61
	v_rcp_f32_e32 v60, v60
	v_add_f32_e32 v61, 1.0, v64
	v_mul_f32_e32 v64, 0xbfb8aa3b, v56
	v_rcp_f32_e32 v61, v61
	v_exp_f32_e32 v64, v64
	v_mul_f32_e32 v60, v62, v60
	v_mul_f32_e32 v54, v60, v54
	v_mul_f32_e32 v60, v63, v61
	v_add_f32_e32 v61, 1.0, v64
	v_rcp_f32_e32 v61, v61
	v_mul_f32_e32 v62, 0xbfb8aa3b, v57
	v_exp_f32_e32 v62, v62
	v_mul_f32_e32 v55, v60, v55
	v_mul_f32_e32 v56, v56, v61
	v_mul_f32_e32 v56, v56, v48
	v_add_f32_e32 v48, 1.0, v62
	v_mul_f32_e32 v60, 0xbfb8aa3b, v58
	v_rcp_f32_e32 v48, v48
	v_exp_f32_e32 v60, v60
	v_mul_f32_e32 v61, 0xbfb8aa3b, v59
	v_exp_f32_e32 v61, v61
	v_mul_f32_e32 v48, v57, v48
	v_add_f32_e32 v57, 1.0, v60
	v_rcp_f32_e32 v57, v57
	v_add_f32_e32 v60, 1.0, v61
	v_rcp_f32_e32 v60, v60
	v_mul_f32_e32 v61, v48, v49
	v_mul_f32_e32 v48, v58, v57
	v_mul_f32_e32 v57, v48, v50
	v_mul_f32_e32 v48, v59, v60
	v_mul_f32_e32 v51, v48, v51
	v_cvt_pk_bf16_f32 v48, v52, v53
	v_cvt_pk_bf16_f32 v49, v54, v55
	v_mul_f32_e32 v54, 0xbfb8aa3b, v44
	v_exp_f32_e32 v54, v54
	v_mul_f32_e32 v55, 0xbfb8aa3b, v45
	v_exp_f32_e32 v55, v55
	v_mad_i64_i32 v[52:53], s[100:101], v66, s48, v[112:113]
	v_lshl_add_u64 v[52:53], v[52:53], 0, v[114:115]
	v_cvt_pk_bf16_f32 v50, v56, v61
	v_cvt_pk_bf16_f32 v51, v57, v51
	global_store_dwordx4 v[52:53], v[48:51], off nt
	s_nop 1
	v_add_f32_e32 v48, 1.0, v54
	v_rcp_f32_e32 v48, v48
	v_add_f32_e32 v49, 1.0, v55
	v_rcp_f32_e32 v49, v49
	v_add_u32_e32 v50, 0x90, v228
	v_mul_f32_e32 v44, v44, v48
	v_mul_f32_e32 v36, v44, v36
	v_mul_f32_e32 v44, v45, v49
	v_mul_f32_e32 v45, 0xbfb8aa3b, v46
	v_exp_f32_e32 v45, v45
	v_mul_f32_e32 v48, 0xbfb8aa3b, v47
	v_exp_f32_e32 v48, v48
	v_mul_f32_e32 v37, v44, v37
	v_add_f32_e32 v44, 1.0, v45
	v_rcp_f32_e32 v44, v44
	v_add_f32_e32 v45, 1.0, v48
	v_mul_f32_e32 v48, 0xbfb8aa3b, v40
	v_rcp_f32_e32 v45, v45
	v_exp_f32_e32 v48, v48
	v_mul_f32_e32 v44, v46, v44
	v_mul_f32_e32 v38, v44, v38
	v_mul_f32_e32 v44, v47, v45
	v_add_f32_e32 v45, 1.0, v48
	v_rcp_f32_e32 v45, v45
	v_mul_f32_e32 v46, 0xbfb8aa3b, v41
	v_exp_f32_e32 v46, v46
	v_mul_f32_e32 v39, v44, v39
	v_mul_f32_e32 v40, v40, v45
	v_mul_f32_e32 v40, v40, v32
	v_add_f32_e32 v32, 1.0, v46
	v_mul_f32_e32 v44, 0xbfb8aa3b, v42
	v_rcp_f32_e32 v32, v32
	v_exp_f32_e32 v44, v44
	v_mul_f32_e32 v45, 0xbfb8aa3b, v43
	v_exp_f32_e32 v45, v45
	v_mul_f32_e32 v32, v41, v32
	v_add_f32_e32 v41, 1.0, v44
	v_rcp_f32_e32 v41, v41
	v_add_f32_e32 v44, 1.0, v45
	v_rcp_f32_e32 v44, v44
	v_mul_f32_e32 v45, v32, v33
	v_mul_f32_e32 v32, v42, v41
	v_mul_f32_e32 v41, v32, v34
	v_mul_f32_e32 v32, v43, v44
	v_mul_f32_e32 v35, v32, v35
	v_cvt_pk_bf16_f32 v32, v36, v37
	v_cvt_pk_bf16_f32 v33, v38, v39
	v_mul_f32_e32 v38, 0xbfb8aa3b, v28
	v_exp_f32_e32 v38, v38
	v_mul_f32_e32 v39, 0xbfb8aa3b, v29
	v_exp_f32_e32 v39, v39
	v_mad_i64_i32 v[36:37], s[100:101], v50, s48, v[112:113]
	v_lshl_add_u64 v[36:37], v[36:37], 0, v[114:115]
	v_cvt_pk_bf16_f32 v34, v40, v45
	v_cvt_pk_bf16_f32 v35, v41, v35
	global_store_dwordx4 v[36:37], v[32:35], off nt
	s_nop 1
	v_add_f32_e32 v32, 1.0, v38
	v_rcp_f32_e32 v32, v32
	v_add_f32_e32 v33, 1.0, v39
	v_rcp_f32_e32 v33, v33
	v_add_u32_e32 v34, 0xa0, v228
	v_mul_f32_e32 v28, v28, v32
	v_mul_f32_e32 v20, v28, v20
	v_mul_f32_e32 v28, v29, v33
	v_mul_f32_e32 v29, 0xbfb8aa3b, v30
	v_exp_f32_e32 v29, v29
	v_mul_f32_e32 v32, 0xbfb8aa3b, v31
	v_exp_f32_e32 v32, v32
	v_mul_f32_e32 v21, v28, v21
	v_add_f32_e32 v28, 1.0, v29
	v_rcp_f32_e32 v28, v28
	v_add_f32_e32 v29, 1.0, v32
	v_mul_f32_e32 v32, 0xbfb8aa3b, v24
	v_rcp_f32_e32 v29, v29
	v_exp_f32_e32 v32, v32
	v_mul_f32_e32 v28, v30, v28
	v_mul_f32_e32 v22, v28, v22
	v_mul_f32_e32 v28, v31, v29
	v_add_f32_e32 v29, 1.0, v32
	v_rcp_f32_e32 v29, v29
	v_mul_f32_e32 v30, 0xbfb8aa3b, v25
	v_exp_f32_e32 v30, v30
	v_mul_f32_e32 v23, v28, v23
	v_mul_f32_e32 v24, v24, v29
	v_mul_f32_e32 v24, v24, v16
	v_add_f32_e32 v16, 1.0, v30
	v_mul_f32_e32 v28, 0xbfb8aa3b, v26
	v_rcp_f32_e32 v16, v16
	v_exp_f32_e32 v28, v28
	v_mul_f32_e32 v29, 0xbfb8aa3b, v27
	v_exp_f32_e32 v29, v29
	v_mul_f32_e32 v16, v25, v16
	v_add_f32_e32 v25, 1.0, v28
	v_rcp_f32_e32 v25, v25
	v_add_f32_e32 v28, 1.0, v29
	v_rcp_f32_e32 v28, v28
	v_mul_f32_e32 v29, v16, v17
	v_mul_f32_e32 v16, v26, v25
	v_mul_f32_e32 v25, v16, v18
	v_mul_f32_e32 v16, v27, v28
	v_mul_f32_e32 v19, v16, v19
	v_cvt_pk_bf16_f32 v16, v20, v21
	v_cvt_pk_bf16_f32 v17, v22, v23
	v_mul_f32_e32 v22, 0xbfb8aa3b, v12
	v_exp_f32_e32 v22, v22
	v_mul_f32_e32 v23, 0xbfb8aa3b, v13
	v_exp_f32_e32 v23, v23
	v_mad_i64_i32 v[20:21], s[100:101], v34, s48, v[112:113]
	v_lshl_add_u64 v[20:21], v[20:21], 0, v[114:115]
	v_cvt_pk_bf16_f32 v18, v24, v29
	v_cvt_pk_bf16_f32 v19, v25, v19
	global_store_dwordx4 v[20:21], v[16:19], off nt
	s_nop 1
	v_add_f32_e32 v16, 1.0, v22
	v_rcp_f32_e32 v16, v16
	v_add_f32_e32 v17, 1.0, v23
	v_rcp_f32_e32 v17, v17
	v_add_u32_e32 v18, 0xb0, v228
	v_mul_f32_e32 v12, v12, v16
	v_mul_f32_e32 v4, v12, v4
	v_mul_f32_e32 v12, v13, v17
	v_mul_f32_e32 v13, 0xbfb8aa3b, v14
	v_exp_f32_e32 v13, v13
	v_mul_f32_e32 v16, 0xbfb8aa3b, v15
	v_exp_f32_e32 v16, v16
	v_mul_f32_e32 v5, v12, v5
	v_add_f32_e32 v12, 1.0, v13
	v_rcp_f32_e32 v12, v12
	v_add_f32_e32 v13, 1.0, v16
	v_mul_f32_e32 v16, 0xbfb8aa3b, v8
	v_rcp_f32_e32 v13, v13
	v_exp_f32_e32 v16, v16
	v_mul_f32_e32 v12, v14, v12
	v_mul_f32_e32 v6, v12, v6
	v_mul_f32_e32 v12, v15, v13
	v_add_f32_e32 v13, 1.0, v16
	v_rcp_f32_e32 v13, v13
	v_mul_f32_e32 v14, 0xbfb8aa3b, v9
	v_exp_f32_e32 v14, v14
	v_mul_f32_e32 v7, v12, v7
	v_mul_f32_e32 v8, v8, v13
	v_mul_f32_e32 v8, v8, v0
	v_add_f32_e32 v0, 1.0, v14
	v_mul_f32_e32 v12, 0xbfb8aa3b, v10
	v_rcp_f32_e32 v0, v0
	v_exp_f32_e32 v12, v12
	v_mul_f32_e32 v13, 0xbfb8aa3b, v11
	v_exp_f32_e32 v13, v13
	v_mul_f32_e32 v0, v9, v0
	v_add_f32_e32 v9, 1.0, v12
	v_rcp_f32_e32 v9, v9
	v_add_f32_e32 v12, 1.0, v13
	v_rcp_f32_e32 v12, v12
	v_mul_f32_e32 v13, v0, v1
	v_mul_f32_e32 v0, v10, v9
	v_mul_f32_e32 v9, v0, v2
	v_mul_f32_e32 v0, v11, v12
	v_mul_f32_e32 v3, v0, v3
	v_cvt_pk_bf16_f32 v0, v4, v5
	v_mad_i64_i32 v[4:5], s[100:101], v18, s48, v[112:113]
	v_lshl_add_u64 v[4:5], v[4:5], 0, v[114:115]
	v_cvt_pk_bf16_f32 v1, v6, v7
	v_cvt_pk_bf16_f32 v2, v8, v13
	v_cvt_pk_bf16_f32 v3, v9, v3
	global_store_dwordx4 v[4:5], v[0:3], off nt

; __device__ __forceinline__ unsigned pk2(float lo, float hi) { return pg8::cvt_pk_bf16(lo, hi); }
; __device__ __forceinline__ float silu_f(float x) { return x * sigmoid_f(x); }
;     __device__ __forceinline__ void operator()(const f32x4 (&acc)[2][2][4][2], const pg8::Unit& u, int wr, int wc, int fr, int fq) const {
;         const int row0 = u.pm * 256 + wr * 64 + fr, col = u.pn * 128 + wc * 32 + 8 * fq;
; #pragma unroll
;         for (int ai = 0; ai < 2; ++ai)
; #pragma unroll
;             for (int m = 0; m < 4; ++m) {
;                 const int row = row0 + ai * 128 + m * 16;
;                 const float rs = sumsq ? rsqrtf(sumsq[row] * (1.f / 1024.f) + EPS) : 1.f;
;                 float o[8];
; #pragma unroll
;                 for (int n = 0; n < 2; ++n)
; #pragma unroll
;                     for (int e = 0; e < 4; ++e) { const float g = acc[ai][0][m][n][e] * rs, up = acc[ai][1][m][n][e] * rs; o[4 * n + e] = silu_f(g) * up; }
;                 u32x4 w; w.x = pk2(o[0], o[1]); w.y = pk2(o[2], o[3]); w.z = pk2(o[4], o[5]); w.w = pk2(o[6], o[7]);
;                 *(u32x4*)(H + (size_t)row * DFF + col) = w;
.LBB0_785:
	v_lshl_add_u32 v144, s0, 8, v148
	v_ashrrev_i32_e32 v145, 31, v144
	v_lshl_add_u64 v[146:147], v[144:145], 2, s[10:11]
	global_load_dword v145, v[146:147], off
	global_load_dword v236, v[146:147], off offset:64
	global_load_dword v237, v[146:147], off offset:128
	global_load_dword v238, v[146:147], off offset:192
	global_load_dword v239, v[146:147], off offset:512
	global_load_dword v240, v[146:147], off offset:576
	global_load_dword v241, v[146:147], off offset:640
	global_load_dword v242, v[146:147], off offset:704
	v_lshl_or_b32 v156, s1, 7, v150
	v_readlane_b32 s0, v235, 33
	v_mov_b32_e32 v161, v114
	v_mov_b32_e32 v114, v123
	v_readlane_b32 s1, v235, 34
	v_mov_b32_e32 v158, v124
	v_mov_b32_e32 v159, v116
	v_mov_b32_e32 v116, v125
	v_mov_b32_e32 v124, v126
	v_mov_b32_e32 v125, v118
	v_mov_b32_e32 v118, v127
	v_mov_b32_e32 v126, v120
	v_mov_b32_e32 v127, v112
	v_mov_b32_e32 v112, v121
	v_mov_b32_e32 v160, v122
	v_mov_b64_e32 v[120:121], s[0:1]
	v_ashrrev_i32_e32 v157, 31, v156
	v_or_b32_e32 v164, 16, v144
	v_mad_i64_i32 v[162:163], s[0:1], v144, s46, v[120:121]
	v_lshlrev_b64 v[122:123], 1, v[156:157]
	v_ashrrev_i32_e32 v165, 31, v164
	v_lshl_add_u64 v[156:157], v[162:163], 0, v[122:123]
	v_lshl_add_u64 v[162:163], v[164:165], 2, s[10:11]
	s_waitcnt vmcnt(0)
	v_fmamk_f32 v145, v145, 0x3a800000, v154
	v_mul_f32_e32 v155, 0x4b800000, v145
	v_cmp_gt_f32_e32 vcc, s45, v145
	s_nop 1
	v_cndmask_b32_e32 v145, v145, v155, vcc
	v_rsq_f32_e32 v145, v145
	s_nop 0
	v_mul_f32_e32 v155, 0x45800000, v145
	v_cndmask_b32_e32 v166, v145, v155, vcc
	v_pk_mul_f32 v[114:115], v[114:115], v[166:167] op_sel_hi:[1,0]
	v_pk_mul_f32 v[158:159], v[158:159], v[166:167] op_sel_hi:[1,0]
	v_pk_mul_f32 v[116:117], v[116:117], v[166:167] op_sel_hi:[1,0]
	v_pk_mul_f32 v[124:125], v[124:125], v[166:167] op_sel_hi:[1,0]
	v_pk_mul_f32 v[118:119], v[118:119], v[166:167] op_sel_hi:[1,0]
	v_pk_mul_f32 v[126:127], v[126:127], v[166:167] op_sel_hi:[1,0]
	v_pk_mul_f32 v[112:113], v[112:113], v[166:167] op_sel_hi:[1,0]
	v_pk_mul_f32 v[160:161], v[160:161], v[166:167] op_sel_hi:[1,0]
	v_mul_f32_e32 v170, 0xbfb8aa3b, v115
	v_mul_f32_e32 v145, 0xbfb8aa3b, v159
	v_mul_f32_e32 v155, 0xbfb8aa3b, v117
	v_mul_f32_e32 v165, 0xbfb8aa3b, v125
	v_mul_f32_e32 v166, 0xbfb8aa3b, v119
	v_mul_f32_e32 v167, 0xbfb8aa3b, v127
	v_mul_f32_e32 v168, 0xbfb8aa3b, v113
	v_mul_f32_e32 v169, 0xbfb8aa3b, v161
	v_exp_f32_e32 v170, v170
	v_exp_f32_e32 v145, v145
	v_exp_f32_e32 v155, v155
	v_exp_f32_e32 v165, v165
	v_exp_f32_e32 v166, v166
	v_exp_f32_e32 v167, v167
	v_exp_f32_e32 v168, v168
	v_exp_f32_e32 v169, v169
	v_add_f32_e32 v170, 1.0, v170
	v_add_f32_e32 v145, 1.0, v145
	v_add_f32_e32 v155, 1.0, v155
	v_add_f32_e32 v165, 1.0, v165
	v_add_f32_e32 v166, 1.0, v166
	v_add_f32_e32 v167, 1.0, v167
	v_add_f32_e32 v168, 1.0, v168
	v_add_f32_e32 v169, 1.0, v169
	v_rcp_f32_e32 v170, v170
	v_rcp_f32_e32 v145, v145
	v_rcp_f32_e32 v155, v155
	v_rcp_f32_e32 v165, v165
	v_rcp_f32_e32 v166, v166
	v_rcp_f32_e32 v167, v167
	v_rcp_f32_e32 v168, v168
	v_rcp_f32_e32 v169, v169
	v_mul_f32_e32 v115, v115, v170
	v_mul_f32_e32 v145, v159, v145
	v_mul_f32_e32 v117, v117, v155
	v_mul_f32_e32 v125, v125, v165
	v_mul_f32_e32 v119, v119, v166
	v_mul_f32_e32 v127, v127, v167
	v_mul_f32_e32 v113, v113, v168
	v_mul_f32_e32 v155, v161, v169
	v_mul_f32_e32 v115, v114, v115
	v_mul_f32_e32 v145, v158, v145
	v_mul_f32_e32 v116, v116, v117
	v_mul_f32_e32 v117, v124, v125
	v_mul_f32_e32 v118, v118, v119
	v_mul_f32_e32 v119, v126, v127
	v_mul_f32_e32 v124, v112, v113
	v_mul_f32_e32 v125, v160, v155
	v_cvt_pk_bf16_f32 v112, v145, v116
	v_cvt_pk_bf16_f32 v113, v117, v118
	v_cvt_pk_bf16_f32 v114, v119, v124
	v_cvt_pk_bf16_f32 v115, v125, v115
	global_store_dwordx4 v[156:157], v[112:115], off nt
	s_nop 0
	s_nop 0
	v_mov_b32_e32 v113, v100
	v_mov_b32_e32 v100, v109
	v_mov_b32_e32 v109, v102
	v_mov_b32_e32 v102, v111
	v_mov_b32_e32 v111, v96
	v_mov_b32_e32 v96, v105
	v_mov_b32_e32 v105, v98
	v_mov_b32_e32 v98, v107
	v_mov_b32_e32 v112, v108
	v_mov_b32_e32 v108, v110
	v_mov_b32_e32 v110, v104
	v_mov_b32_e32 v104, v106
	v_or_b32_e32 v106, 32, v144
	v_mad_i64_i32 v[114:115], s[0:1], v164, s46, v[120:121]
	v_lshl_add_u64 v[114:115], v[114:115], 0, v[122:123]
	s_nop 0
	v_fmamk_f32 v107, v236, 0x3a800000, v154
	v_mul_f32_e32 v116, 0x4b800000, v107
	v_cmp_gt_f32_e32 vcc, s45, v107
	s_nop 1
	v_cndmask_b32_e32 v107, v107, v116, vcc
	v_rsq_f32_e32 v118, v107
	v_ashrrev_i32_e32 v107, 31, v106
	v_lshl_add_u64 v[116:117], v[106:107], 2, s[10:11]
	v_mul_f32_e32 v107, 0x45800000, v118
	v_cndmask_b32_e32 v118, v118, v107, vcc
	v_pk_mul_f32 v[98:99], v[98:99], v[118:119] op_sel_hi:[1,0]
	v_pk_mul_f32 v[112:113], v[112:113], v[118:119] op_sel_hi:[1,0]
	v_pk_mul_f32 v[100:101], v[100:101], v[118:119] op_sel_hi:[1,0]
	v_pk_mul_f32 v[108:109], v[108:109], v[118:119] op_sel_hi:[1,0]
	v_pk_mul_f32 v[102:103], v[102:103], v[118:119] op_sel_hi:[1,0]
	v_pk_mul_f32 v[110:111], v[110:111], v[118:119] op_sel_hi:[1,0]
	v_pk_mul_f32 v[96:97], v[96:97], v[118:119] op_sel_hi:[1,0]
	v_pk_mul_f32 v[104:105], v[104:105], v[118:119] op_sel_hi:[1,0]
	v_mul_f32_e32 v145, 0xbfb8aa3b, v99
	v_mul_f32_e32 v107, 0xbfb8aa3b, v113
	v_mul_f32_e32 v118, 0xbfb8aa3b, v101
	v_mul_f32_e32 v119, 0xbfb8aa3b, v109
	v_mul_f32_e32 v124, 0xbfb8aa3b, v103
	v_mul_f32_e32 v125, 0xbfb8aa3b, v111
	v_mul_f32_e32 v126, 0xbfb8aa3b, v97
	v_mul_f32_e32 v127, 0xbfb8aa3b, v105
	v_exp_f32_e32 v145, v145
	v_exp_f32_e32 v107, v107
	v_exp_f32_e32 v118, v118
	v_exp_f32_e32 v119, v119
	v_exp_f32_e32 v124, v124
	v_exp_f32_e32 v125, v125
	v_exp_f32_e32 v126, v126
	v_exp_f32_e32 v127, v127
	v_add_f32_e32 v145, 1.0, v145
; __device__ __forceinline__ unsigned pk2(float lo, float hi) { return pg8::cvt_pk_bf16(lo, hi); }
; __device__ __forceinline__ float silu_f(float x) { return x * sigmoid_f(x); }
;     __device__ __forceinline__ void operator()(const f32x4 (&acc)[2][2][4][2], const pg8::Unit& u, int wr, int wc, int fr, int fq) const {
;         const int row0 = u.pm * 256 + wr * 64 + fr, col = u.pn * 128 + wc * 32 + 8 * fq;
; #pragma unroll
;         for (int ai = 0; ai < 2; ++ai)
; #pragma unroll
;             for (int m = 0; m < 4; ++m) {
;                 const int row = row0 + ai * 128 + m * 16;
;                 const float rs = sumsq ? rsqrtf(sumsq[row] * (1.f / 1024.f) + EPS) : 1.f;
;                 float o[8];
; #pragma unroll
;                 for (int n = 0; n < 2; ++n)
; #pragma unroll
;                     for (int e = 0; e < 4; ++e) { const float g = acc[ai][0][m][n][e] * rs, up = acc[ai][1][m][n][e] * rs; o[4 * n + e] = silu_f(g) * up; }
;                 u32x4 w; w.x = pk2(o[0], o[1]); w.y = pk2(o[2], o[3]); w.z = pk2(o[4], o[5]); w.w = pk2(o[6], o[7]);
;                 *(u32x4*)(H + (size_t)row * DFF + col) = w;
	v_add_f32_e32 v107, 1.0, v107
	v_add_f32_e32 v118, 1.0, v118
	v_add_f32_e32 v119, 1.0, v119
	v_add_f32_e32 v124, 1.0, v124
	v_add_f32_e32 v125, 1.0, v125
	v_add_f32_e32 v126, 1.0, v126
	v_add_f32_e32 v127, 1.0, v127
	v_rcp_f32_e32 v145, v145
	v_rcp_f32_e32 v107, v107
	v_rcp_f32_e32 v118, v118
	v_rcp_f32_e32 v119, v119
	v_rcp_f32_e32 v124, v124
	v_rcp_f32_e32 v125, v125
	v_rcp_f32_e32 v126, v126
	v_rcp_f32_e32 v127, v127
	v_mul_f32_e32 v99, v99, v145
	v_mul_f32_e32 v107, v113, v107
	v_mul_f32_e32 v101, v101, v118
	v_mul_f32_e32 v109, v109, v119
	v_mul_f32_e32 v103, v103, v124
	v_mul_f32_e32 v111, v111, v125
	v_mul_f32_e32 v97, v97, v126
	v_mul_f32_e32 v105, v105, v127
	v_mul_f32_e32 v99, v98, v99
	v_mul_f32_e32 v107, v112, v107
	v_mul_f32_e32 v100, v100, v101
	v_mul_f32_e32 v101, v108, v109
	v_mul_f32_e32 v102, v102, v103
	v_mul_f32_e32 v103, v110, v111
	v_mul_f32_e32 v108, v96, v97
	v_mul_f32_e32 v104, v104, v105
	v_cvt_pk_bf16_f32 v96, v107, v100
	v_cvt_pk_bf16_f32 v97, v101, v102
	v_cvt_pk_bf16_f32 v98, v103, v108
	v_cvt_pk_bf16_f32 v99, v104, v99
	global_store_dwordx4 v[114:115], v[96:99], off nt
	s_nop 0
	s_nop 0
	v_mov_b32_e32 v97, v84
	v_mov_b32_e32 v84, v93
	v_mov_b32_e32 v93, v86
	v_mov_b32_e32 v86, v95
	v_mov_b32_e32 v95, v80
	v_mov_b32_e32 v80, v89
	v_mov_b32_e32 v89, v82
	v_mov_b32_e32 v82, v91
	v_mov_b32_e32 v96, v92
	v_mov_b32_e32 v92, v94
	v_mov_b32_e32 v94, v88
	v_mov_b32_e32 v88, v90
	v_or_b32_e32 v90, 48, v144
	v_mad_i64_i32 v[98:99], s[0:1], v106, s46, v[120:121]
	v_lshl_add_u64 v[98:99], v[98:99], 0, v[122:123]
	s_nop 0
	v_fmamk_f32 v91, v237, 0x3a800000, v154
	v_mul_f32_e32 v100, 0x4b800000, v91
	v_cmp_gt_f32_e32 vcc, s45, v91
	s_nop 1
	v_cndmask_b32_e32 v91, v91, v100, vcc
	v_rsq_f32_e32 v102, v91
	v_ashrrev_i32_e32 v91, 31, v90
	v_lshl_add_u64 v[100:101], v[90:91], 2, s[10:11]
	v_mul_f32_e32 v91, 0x45800000, v102
	v_cndmask_b32_e32 v102, v102, v91, vcc
	v_pk_mul_f32 v[82:83], v[82:83], v[102:103] op_sel_hi:[1,0]
	v_pk_mul_f32 v[96:97], v[96:97], v[102:103] op_sel_hi:[1,0]
	v_pk_mul_f32 v[84:85], v[84:85], v[102:103] op_sel_hi:[1,0]
	v_pk_mul_f32 v[92:93], v[92:93], v[102:103] op_sel_hi:[1,0]
	v_pk_mul_f32 v[86:87], v[86:87], v[102:103] op_sel_hi:[1,0]
	v_pk_mul_f32 v[94:95], v[94:95], v[102:103] op_sel_hi:[1,0]
	v_pk_mul_f32 v[80:81], v[80:81], v[102:103] op_sel_hi:[1,0]
	v_pk_mul_f32 v[88:89], v[88:89], v[102:103] op_sel_hi:[1,0]
	v_mul_f32_e32 v108, 0xbfb8aa3b, v83
	v_mul_f32_e32 v91, 0xbfb8aa3b, v97
	v_mul_f32_e32 v102, 0xbfb8aa3b, v85
	v_mul_f32_e32 v103, 0xbfb8aa3b, v93
	v_mul_f32_e32 v104, 0xbfb8aa3b, v87
	v_mul_f32_e32 v105, 0xbfb8aa3b, v95
	v_mul_f32_e32 v106, 0xbfb8aa3b, v81
	v_mul_f32_e32 v107, 0xbfb8aa3b, v89
	v_exp_f32_e32 v108, v108
	v_exp_f32_e32 v91, v91
	v_exp_f32_e32 v102, v102
	v_exp_f32_e32 v103, v103
	v_exp_f32_e32 v104, v104
	v_exp_f32_e32 v105, v105
	v_exp_f32_e32 v106, v106
	v_exp_f32_e32 v107, v107
	v_add_f32_e32 v108, 1.0, v108
	v_add_f32_e32 v91, 1.0, v91
	v_add_f32_e32 v102, 1.0, v102
	v_add_f32_e32 v103, 1.0, v103
	v_add_f32_e32 v104, 1.0, v104
	v_add_f32_e32 v105, 1.0, v105
	v_add_f32_e32 v106, 1.0, v106
	v_add_f32_e32 v107, 1.0, v107
	v_rcp_f32_e32 v108, v108
	v_rcp_f32_e32 v91, v91
	v_rcp_f32_e32 v102, v102
	v_rcp_f32_e32 v103, v103
	v_rcp_f32_e32 v104, v104
	v_rcp_f32_e32 v105, v105
	v_rcp_f32_e32 v106, v106
	v_rcp_f32_e32 v107, v107
	v_mul_f32_e32 v83, v83, v108
	v_mul_f32_e32 v91, v97, v91
	v_mul_f32_e32 v85, v85, v102
	v_mul_f32_e32 v93, v93, v103
	v_mul_f32_e32 v87, v87, v104
	v_mul_f32_e32 v95, v95, v105
	v_mul_f32_e32 v81, v81, v106
	v_mul_f32_e32 v89, v89, v107
	v_mul_f32_e32 v83, v82, v83
	v_mul_f32_e32 v91, v96, v91
	v_mul_f32_e32 v84, v84, v85
	v_mul_f32_e32 v85, v92, v93
	v_mul_f32_e32 v86, v86, v87
	v_mul_f32_e32 v87, v94, v95
	v_mul_f32_e32 v92, v80, v81
	v_mul_f32_e32 v88, v88, v89
	v_cvt_pk_bf16_f32 v80, v91, v84
	v_cvt_pk_bf16_f32 v81, v85, v86
	v_cvt_pk_bf16_f32 v82, v87, v92
	v_cvt_pk_bf16_f32 v83, v88, v83
	global_store_dwordx4 v[98:99], v[80:83], off nt
	s_nop 0
	s_nop 0
	v_mov_b32_e32 v80, v76
	v_mov_b32_e32 v76, v78
	v_mov_b32_e32 v78, v68
	v_mov_b32_e32 v68, v70
	v_mov_b32_e32 v81, v72
	v_mov_b32_e32 v72, v77
	v_mov_b32_e32 v77, v74
	v_mov_b32_e32 v74, v79
	v_mov_b32_e32 v79, v64
	v_mov_b32_e32 v64, v69
	v_mov_b32_e32 v69, v66
	v_mov_b32_e32 v66, v71
	s_nop 0
	v_fmamk_f32 v70, v238, 0x3a800000, v154
	v_mul_f32_e32 v71, 0x4b800000, v70
	v_cmp_gt_f32_e32 vcc, s45, v70
	s_nop 1
	v_cndmask_b32_e32 v70, v70, v71, vcc
	v_rsq_f32_e32 v82, v70
	v_mad_i64_i32 v[70:71], s[0:1], v90, s46, v[120:121]
	v_lshl_add_u64 v[70:71], v[70:71], 0, v[122:123]
	v_mul_f32_e32 v83, 0x45800000, v82
	v_cndmask_b32_e32 v82, v82, v83, vcc
	v_pk_mul_f32 v[66:67], v[66:67], v[82:83] op_sel_hi:[1,0]
	v_pk_mul_f32 v[80:81], v[80:81], v[82:83] op_sel_hi:[1,0]
	v_pk_mul_f32 v[72:73], v[72:73], v[82:83] op_sel_hi:[1,0]
	v_pk_mul_f32 v[76:77], v[76:77], v[82:83] op_sel_hi:[1,0]
	v_pk_mul_f32 v[74:75], v[74:75], v[82:83] op_sel_hi:[1,0]
	v_pk_mul_f32 v[78:79], v[78:79], v[82:83] op_sel_hi:[1,0]
	v_pk_mul_f32 v[64:65], v[64:65], v[82:83] op_sel_hi:[1,0]
	v_pk_mul_f32 v[68:69], v[68:69], v[82:83] op_sel_hi:[1,0]
	v_mul_f32_e32 v89, 0xbfb8aa3b, v67
	v_mul_f32_e32 v82, 0xbfb8aa3b, v81
	v_mul_f32_e32 v83, 0xbfb8aa3b, v73
	v_mul_f32_e32 v84, 0xbfb8aa3b, v77
	v_mul_f32_e32 v85, 0xbfb8aa3b, v75
	v_mul_f32_e32 v86, 0xbfb8aa3b, v79
	v_mul_f32_e32 v87, 0xbfb8aa3b, v65
	v_mul_f32_e32 v88, 0xbfb8aa3b, v69
	v_exp_f32_e32 v89, v89
	v_exp_f32_e32 v82, v82
	v_exp_f32_e32 v83, v83
	v_exp_f32_e32 v84, v84
	v_exp_f32_e32 v85, v85
	v_exp_f32_e32 v86, v86
	v_exp_f32_e32 v87, v87
	v_exp_f32_e32 v88, v88
; __device__ __forceinline__ unsigned pk2(float lo, float hi) { return pg8::cvt_pk_bf16(lo, hi); }
; __device__ __forceinline__ float silu_f(float x) { return x * sigmoid_f(x); }
;     __device__ __forceinline__ void operator()(const f32x4 (&acc)[2][2][4][2], const pg8::Unit& u, int wr, int wc, int fr, int fq) const {
;         const int row0 = u.pm * 256 + wr * 64 + fr, col = u.pn * 128 + wc * 32 + 8 * fq;
; #pragma unroll
;         for (int ai = 0; ai < 2; ++ai)
; #pragma unroll
;             for (int m = 0; m < 4; ++m) {
;                 const int row = row0 + ai * 128 + m * 16;
;                 const float rs = sumsq ? rsqrtf(sumsq[row] * (1.f / 1024.f) + EPS) : 1.f;
;                 float o[8];
; #pragma unroll
;                 for (int n = 0; n < 2; ++n)
; #pragma unroll
;                     for (int e = 0; e < 4; ++e) { const float g = acc[ai][0][m][n][e] * rs, up = acc[ai][1][m][n][e] * rs; o[4 * n + e] = silu_f(g) * up; }
;                 u32x4 w; w.x = pk2(o[0], o[1]); w.y = pk2(o[2], o[3]); w.z = pk2(o[4], o[5]); w.w = pk2(o[6], o[7]);
;                 *(u32x4*)(H + (size_t)row * DFF + col) = w;
	v_add_f32_e32 v89, 1.0, v89
	v_add_f32_e32 v82, 1.0, v82
	v_add_f32_e32 v83, 1.0, v83
	v_add_f32_e32 v84, 1.0, v84
	v_add_f32_e32 v85, 1.0, v85
	v_add_f32_e32 v86, 1.0, v86
	v_add_f32_e32 v87, 1.0, v87
	v_add_f32_e32 v88, 1.0, v88
	v_rcp_f32_e32 v89, v89
	v_rcp_f32_e32 v82, v82
	v_rcp_f32_e32 v83, v83
	v_rcp_f32_e32 v84, v84
	v_rcp_f32_e32 v85, v85
	v_rcp_f32_e32 v86, v86
	v_rcp_f32_e32 v87, v87
	v_rcp_f32_e32 v88, v88
	v_mul_f32_e32 v67, v67, v89
	v_mul_f32_e32 v81, v81, v82
	v_mul_f32_e32 v73, v73, v83
	v_mul_f32_e32 v77, v77, v84
	v_mul_f32_e32 v75, v75, v85
	v_mul_f32_e32 v79, v79, v86
	v_mul_f32_e32 v65, v65, v87
	v_mul_f32_e32 v69, v69, v88
	v_mul_f32_e32 v67, v66, v67
	v_mul_f32_e32 v80, v80, v81
	v_mul_f32_e32 v72, v72, v73
	v_mul_f32_e32 v73, v76, v77
	v_mul_f32_e32 v74, v74, v75
	v_mul_f32_e32 v75, v78, v79
	v_mul_f32_e32 v76, v64, v65
	v_mul_f32_e32 v68, v68, v69
	v_cvt_pk_bf16_f32 v64, v80, v72
	v_cvt_pk_bf16_f32 v65, v73, v74
	v_cvt_pk_bf16_f32 v66, v75, v76
	v_cvt_pk_bf16_f32 v67, v68, v67
	global_store_dwordx4 v[70:71], v[64:67], off nt
	s_nop 0
	s_nop 0
	v_mov_b32_e32 v65, v56
	v_mov_b32_e32 v56, v61
	v_mov_b32_e32 v61, v58
	v_mov_b32_e32 v58, v63
	v_mov_b32_e32 v63, v48
	v_mov_b32_e32 v48, v53
	v_mov_b32_e32 v53, v50
	v_mov_b32_e32 v50, v55
	v_mov_b32_e32 v64, v60
	v_mov_b32_e32 v60, v62
	v_mov_b32_e32 v62, v52
	v_mov_b32_e32 v52, v54
	v_add_u32_e32 v54, 0x80, v144
	s_nop 0
	v_fmamk_f32 v55, v239, 0x3a800000, v154
	v_mul_f32_e32 v66, 0x4b800000, v55
	v_cmp_gt_f32_e32 vcc, s45, v55
	s_nop 1
	v_cndmask_b32_e32 v55, v55, v66, vcc
	v_rsq_f32_e32 v66, v55
	v_mad_i64_i32 v[54:55], s[0:1], v54, s46, v[120:121]
	v_lshl_add_u64 v[54:55], v[54:55], 0, v[122:123]
	v_mul_f32_e32 v67, 0x45800000, v66
	v_cndmask_b32_e32 v66, v66, v67, vcc
	v_pk_mul_f32 v[50:51], v[50:51], v[66:67] op_sel_hi:[1,0]
	v_pk_mul_f32 v[64:65], v[64:65], v[66:67] op_sel_hi:[1,0]
	v_pk_mul_f32 v[56:57], v[56:57], v[66:67] op_sel_hi:[1,0]
	v_pk_mul_f32 v[60:61], v[60:61], v[66:67] op_sel_hi:[1,0]
	v_pk_mul_f32 v[58:59], v[58:59], v[66:67] op_sel_hi:[1,0]
	v_pk_mul_f32 v[62:63], v[62:63], v[66:67] op_sel_hi:[1,0]
	v_pk_mul_f32 v[48:49], v[48:49], v[66:67] op_sel_hi:[1,0]
	v_pk_mul_f32 v[52:53], v[52:53], v[66:67] op_sel_hi:[1,0]
	v_mul_f32_e32 v73, 0xbfb8aa3b, v51
	v_mul_f32_e32 v66, 0xbfb8aa3b, v65
	v_mul_f32_e32 v67, 0xbfb8aa3b, v57
	v_mul_f32_e32 v68, 0xbfb8aa3b, v61
	v_mul_f32_e32 v69, 0xbfb8aa3b, v59
	v_mul_f32_e32 v70, 0xbfb8aa3b, v63
	v_mul_f32_e32 v71, 0xbfb8aa3b, v49
	v_mul_f32_e32 v72, 0xbfb8aa3b, v53
	v_exp_f32_e32 v73, v73
	v_exp_f32_e32 v66, v66
	v_exp_f32_e32 v67, v67
	v_exp_f32_e32 v68, v68
	v_exp_f32_e32 v69, v69
	v_exp_f32_e32 v70, v70
	v_exp_f32_e32 v71, v71
	v_exp_f32_e32 v72, v72
	v_add_f32_e32 v73, 1.0, v73
	v_add_f32_e32 v66, 1.0, v66
	v_add_f32_e32 v67, 1.0, v67
	v_add_f32_e32 v68, 1.0, v68
	v_add_f32_e32 v69, 1.0, v69
	v_add_f32_e32 v70, 1.0, v70
	v_add_f32_e32 v71, 1.0, v71
	v_add_f32_e32 v72, 1.0, v72
	v_rcp_f32_e32 v73, v73
	v_rcp_f32_e32 v66, v66
	v_rcp_f32_e32 v67, v67
	v_rcp_f32_e32 v68, v68
	v_rcp_f32_e32 v69, v69
	v_rcp_f32_e32 v70, v70
	v_rcp_f32_e32 v71, v71
	v_rcp_f32_e32 v72, v72
	v_mul_f32_e32 v51, v51, v73
	v_mul_f32_e32 v65, v65, v66
	v_mul_f32_e32 v57, v57, v67
	v_mul_f32_e32 v61, v61, v68
	v_mul_f32_e32 v59, v59, v69
	v_mul_f32_e32 v63, v63, v70
	v_mul_f32_e32 v49, v49, v71
	v_mul_f32_e32 v53, v53, v72
	v_mul_f32_e32 v51, v50, v51
	v_mul_f32_e32 v64, v64, v65
	v_mul_f32_e32 v56, v56, v57
	v_mul_f32_e32 v57, v60, v61
	v_mul_f32_e32 v58, v58, v59
	v_mul_f32_e32 v59, v62, v63
	v_mul_f32_e32 v60, v48, v49
	v_mul_f32_e32 v52, v52, v53
	v_cvt_pk_bf16_f32 v48, v64, v56
	v_cvt_pk_bf16_f32 v49, v57, v58
	v_cvt_pk_bf16_f32 v50, v59, v60
	v_cvt_pk_bf16_f32 v51, v52, v51
	global_store_dwordx4 v[54:55], v[48:51], off nt
	s_nop 0
	s_nop 0
	v_mov_b32_e32 v49, v40
	v_mov_b32_e32 v40, v45
	v_mov_b32_e32 v45, v42
	v_mov_b32_e32 v42, v47
	v_mov_b32_e32 v47, v32
	v_mov_b32_e32 v32, v37
	v_mov_b32_e32 v37, v34
	v_mov_b32_e32 v34, v39
	v_mov_b32_e32 v48, v44
	v_mov_b32_e32 v44, v46
	v_mov_b32_e32 v46, v36
	v_mov_b32_e32 v36, v38
	v_add_u32_e32 v38, 0x90, v144
	s_nop 0
	v_fmamk_f32 v39, v240, 0x3a800000, v154
	v_mul_f32_e32 v50, 0x4b800000, v39
	v_cmp_gt_f32_e32 vcc, s45, v39
	s_nop 1
	v_cndmask_b32_e32 v39, v39, v50, vcc
	v_rsq_f32_e32 v50, v39
	v_mad_i64_i32 v[38:39], s[0:1], v38, s46, v[120:121]
	v_lshl_add_u64 v[38:39], v[38:39], 0, v[122:123]
	v_mul_f32_e32 v51, 0x45800000, v50
	v_cndmask_b32_e32 v50, v50, v51, vcc
	v_pk_mul_f32 v[34:35], v[34:35], v[50:51] op_sel_hi:[1,0]
	v_pk_mul_f32 v[48:49], v[48:49], v[50:51] op_sel_hi:[1,0]
	v_pk_mul_f32 v[40:41], v[40:41], v[50:51] op_sel_hi:[1,0]
	v_pk_mul_f32 v[44:45], v[44:45], v[50:51] op_sel_hi:[1,0]
	v_pk_mul_f32 v[42:43], v[42:43], v[50:51] op_sel_hi:[1,0]
	v_pk_mul_f32 v[46:47], v[46:47], v[50:51] op_sel_hi:[1,0]
	v_pk_mul_f32 v[32:33], v[32:33], v[50:51] op_sel_hi:[1,0]
	v_pk_mul_f32 v[36:37], v[36:37], v[50:51] op_sel_hi:[1,0]
	v_mul_f32_e32 v57, 0xbfb8aa3b, v35
	v_mul_f32_e32 v50, 0xbfb8aa3b, v49
	v_mul_f32_e32 v51, 0xbfb8aa3b, v41
	v_mul_f32_e32 v52, 0xbfb8aa3b, v45
	v_mul_f32_e32 v53, 0xbfb8aa3b, v43
	v_mul_f32_e32 v54, 0xbfb8aa3b, v47
	v_mul_f32_e32 v55, 0xbfb8aa3b, v33
	v_mul_f32_e32 v56, 0xbfb8aa3b, v37
	v_exp_f32_e32 v57, v57
	v_exp_f32_e32 v50, v50
	v_exp_f32_e32 v51, v51
	v_exp_f32_e32 v52, v52
	v_exp_f32_e32 v53, v53
	v_exp_f32_e32 v54, v54
	v_exp_f32_e32 v55, v55
	v_exp_f32_e32 v56, v56
	v_add_f32_e32 v57, 1.0, v57
	v_add_f32_e32 v50, 1.0, v50
	v_add_f32_e32 v51, 1.0, v51
	v_add_f32_e32 v52, 1.0, v52
	v_add_f32_e32 v53, 1.0, v53
	v_add_f32_e32 v54, 1.0, v54
	v_add_f32_e32 v55, 1.0, v55
; __device__ __forceinline__ unsigned pk2(float lo, float hi) { return pg8::cvt_pk_bf16(lo, hi); }
; __device__ __forceinline__ float silu_f(float x) { return x * sigmoid_f(x); }
;     __device__ __forceinline__ void operator()(const f32x4 (&acc)[2][2][4][2], const pg8::Unit& u, int wr, int wc, int fr, int fq) const {
;         const int row0 = u.pm * 256 + wr * 64 + fr, col = u.pn * 128 + wc * 32 + 8 * fq;
; #pragma unroll
;         for (int ai = 0; ai < 2; ++ai)
; #pragma unroll
;             for (int m = 0; m < 4; ++m) {
;                 const int row = row0 + ai * 128 + m * 16;
;                 const float rs = sumsq ? rsqrtf(sumsq[row] * (1.f / 1024.f) + EPS) : 1.f;
;                 float o[8];
; #pragma unroll
;                 for (int n = 0; n < 2; ++n)
; #pragma unroll
;                     for (int e = 0; e < 4; ++e) { const float g = acc[ai][0][m][n][e] * rs, up = acc[ai][1][m][n][e] * rs; o[4 * n + e] = silu_f(g) * up; }
;                 u32x4 w; w.x = pk2(o[0], o[1]); w.y = pk2(o[2], o[3]); w.z = pk2(o[4], o[5]); w.w = pk2(o[6], o[7]);
;                 *(u32x4*)(H + (size_t)row * DFF + col) = w;
	v_add_f32_e32 v56, 1.0, v56
	v_rcp_f32_e32 v57, v57
	v_rcp_f32_e32 v50, v50
	v_rcp_f32_e32 v51, v51
	v_rcp_f32_e32 v52, v52
	v_rcp_f32_e32 v53, v53
	v_rcp_f32_e32 v54, v54
	v_rcp_f32_e32 v55, v55
	v_rcp_f32_e32 v56, v56
	v_mul_f32_e32 v35, v35, v57
	v_mul_f32_e32 v49, v49, v50
	v_mul_f32_e32 v41, v41, v51
	v_mul_f32_e32 v45, v45, v52
	v_mul_f32_e32 v43, v43, v53
	v_mul_f32_e32 v47, v47, v54
	v_mul_f32_e32 v33, v33, v55
	v_mul_f32_e32 v37, v37, v56
	v_mul_f32_e32 v35, v34, v35
	v_mul_f32_e32 v48, v48, v49
	v_mul_f32_e32 v40, v40, v41
	v_mul_f32_e32 v41, v44, v45
	v_mul_f32_e32 v42, v42, v43
	v_mul_f32_e32 v43, v46, v47
	v_mul_f32_e32 v44, v32, v33
	v_mul_f32_e32 v36, v36, v37
	v_cvt_pk_bf16_f32 v32, v48, v40
	v_cvt_pk_bf16_f32 v33, v41, v42
	v_cvt_pk_bf16_f32 v34, v43, v44
	v_cvt_pk_bf16_f32 v35, v36, v35
	global_store_dwordx4 v[38:39], v[32:35], off nt
	s_nop 0
	s_nop 0
	v_mov_b32_e32 v33, v24
	v_mov_b32_e32 v24, v29
	v_mov_b32_e32 v29, v26
	v_mov_b32_e32 v26, v31
	v_mov_b32_e32 v31, v16
	v_mov_b32_e32 v16, v21
	v_mov_b32_e32 v21, v18
	v_mov_b32_e32 v18, v23
	v_mov_b32_e32 v32, v28
	v_mov_b32_e32 v28, v30
	v_mov_b32_e32 v30, v20
	v_mov_b32_e32 v20, v22
	v_add_u32_e32 v22, 0xa0, v144
	s_nop 0
	v_fmamk_f32 v23, v241, 0x3a800000, v154
	v_mul_f32_e32 v34, 0x4b800000, v23
	v_cmp_gt_f32_e32 vcc, s45, v23
	s_nop 1
	v_cndmask_b32_e32 v23, v23, v34, vcc
	v_rsq_f32_e32 v34, v23
	v_mad_i64_i32 v[22:23], s[0:1], v22, s46, v[120:121]
	v_lshl_add_u64 v[22:23], v[22:23], 0, v[122:123]
	v_mul_f32_e32 v35, 0x45800000, v34
	v_cndmask_b32_e32 v34, v34, v35, vcc
	v_pk_mul_f32 v[18:19], v[18:19], v[34:35] op_sel_hi:[1,0]
	v_pk_mul_f32 v[32:33], v[32:33], v[34:35] op_sel_hi:[1,0]
	v_pk_mul_f32 v[24:25], v[24:25], v[34:35] op_sel_hi:[1,0]
	v_pk_mul_f32 v[28:29], v[28:29], v[34:35] op_sel_hi:[1,0]
	v_pk_mul_f32 v[26:27], v[26:27], v[34:35] op_sel_hi:[1,0]
	v_pk_mul_f32 v[30:31], v[30:31], v[34:35] op_sel_hi:[1,0]
	v_pk_mul_f32 v[16:17], v[16:17], v[34:35] op_sel_hi:[1,0]
	v_pk_mul_f32 v[20:21], v[20:21], v[34:35] op_sel_hi:[1,0]
	v_mul_f32_e32 v41, 0xbfb8aa3b, v19
	v_mul_f32_e32 v34, 0xbfb8aa3b, v33
	v_mul_f32_e32 v35, 0xbfb8aa3b, v25
	v_mul_f32_e32 v36, 0xbfb8aa3b, v29
	v_mul_f32_e32 v37, 0xbfb8aa3b, v27
	v_mul_f32_e32 v38, 0xbfb8aa3b, v31
	v_mul_f32_e32 v39, 0xbfb8aa3b, v17
	v_mul_f32_e32 v40, 0xbfb8aa3b, v21
	v_exp_f32_e32 v41, v41
	v_exp_f32_e32 v34, v34
	v_exp_f32_e32 v35, v35
	v_exp_f32_e32 v36, v36
	v_exp_f32_e32 v37, v37
	v_exp_f32_e32 v38, v38
	v_exp_f32_e32 v39, v39
	v_exp_f32_e32 v40, v40
	v_add_f32_e32 v41, 1.0, v41
	v_add_f32_e32 v34, 1.0, v34
	v_add_f32_e32 v35, 1.0, v35
	v_add_f32_e32 v36, 1.0, v36
	v_add_f32_e32 v37, 1.0, v37
	v_add_f32_e32 v38, 1.0, v38
	v_add_f32_e32 v39, 1.0, v39
	v_add_f32_e32 v40, 1.0, v40
	v_rcp_f32_e32 v41, v41
	v_rcp_f32_e32 v34, v34
	v_rcp_f32_e32 v35, v35
	v_rcp_f32_e32 v36, v36
	v_rcp_f32_e32 v37, v37
	v_rcp_f32_e32 v38, v38
	v_rcp_f32_e32 v39, v39
	v_rcp_f32_e32 v40, v40
	v_mul_f32_e32 v19, v19, v41
	v_mul_f32_e32 v33, v33, v34
	v_mul_f32_e32 v25, v25, v35
	v_mul_f32_e32 v29, v29, v36
	v_mul_f32_e32 v27, v27, v37
	v_mul_f32_e32 v31, v31, v38
	v_mul_f32_e32 v17, v17, v39
	v_mul_f32_e32 v21, v21, v40
	v_mul_f32_e32 v19, v18, v19
	v_mul_f32_e32 v32, v32, v33
	v_mul_f32_e32 v24, v24, v25
	v_mul_f32_e32 v25, v28, v29
	v_mul_f32_e32 v26, v26, v27
	v_mul_f32_e32 v27, v30, v31
	v_mul_f32_e32 v28, v16, v17
	v_mul_f32_e32 v20, v20, v21
	v_cvt_pk_bf16_f32 v16, v32, v24
	v_cvt_pk_bf16_f32 v17, v25, v26
	v_cvt_pk_bf16_f32 v18, v27, v28
	v_cvt_pk_bf16_f32 v19, v20, v19
	global_store_dwordx4 v[22:23], v[16:19], off nt
	s_nop 0
	s_andn2_b64 vcc, exec, s[4:5]
	v_mov_b32_e32 v17, v8
	v_mov_b32_e32 v8, v13
	v_mov_b32_e32 v13, v10
	v_mov_b32_e32 v10, v15
	v_mov_b32_e32 v15, v0
	v_mov_b32_e32 v0, v5
	v_mov_b32_e32 v5, v2
	v_mov_b32_e32 v2, v7
	v_mov_b32_e32 v16, v12
	v_mov_b32_e32 v12, v14
	v_mov_b32_e32 v14, v4
	v_mov_b32_e32 v4, v6
	v_add_u32_e32 v6, 0xb0, v144
	s_nop 0
	v_fmamk_f32 v7, v242, 0x3a800000, v154
	v_mul_f32_e32 v18, 0x4b800000, v7
	v_cmp_gt_f32_e64 s[0:1], s45, v7
	s_nop 1
	v_cndmask_b32_e64 v7, v7, v18, s[0:1]
	v_rsq_f32_e32 v18, v7
	v_mad_i64_i32 v[6:7], s[22:23], v6, s46, v[120:121]
	v_lshl_add_u64 v[6:7], v[6:7], 0, v[122:123]
	v_mul_f32_e32 v19, 0x45800000, v18
	v_cndmask_b32_e64 v18, v18, v19, s[0:1]
	v_pk_mul_f32 v[2:3], v[2:3], v[18:19] op_sel_hi:[1,0]
	v_pk_mul_f32 v[16:17], v[16:17], v[18:19] op_sel_hi:[1,0]
	v_pk_mul_f32 v[8:9], v[8:9], v[18:19] op_sel_hi:[1,0]
	v_pk_mul_f32 v[12:13], v[12:13], v[18:19] op_sel_hi:[1,0]
	v_pk_mul_f32 v[10:11], v[10:11], v[18:19] op_sel_hi:[1,0]
	v_pk_mul_f32 v[14:15], v[14:15], v[18:19] op_sel_hi:[1,0]
	v_pk_mul_f32 v[0:1], v[0:1], v[18:19] op_sel_hi:[1,0]
	v_pk_mul_f32 v[4:5], v[4:5], v[18:19] op_sel_hi:[1,0]
	v_mul_f32_e32 v25, 0xbfb8aa3b, v3
	v_mul_f32_e32 v18, 0xbfb8aa3b, v17
	v_mul_f32_e32 v19, 0xbfb8aa3b, v9
	v_mul_f32_e32 v20, 0xbfb8aa3b, v13
	v_mul_f32_e32 v21, 0xbfb8aa3b, v11
	v_mul_f32_e32 v22, 0xbfb8aa3b, v15
	v_mul_f32_e32 v23, 0xbfb8aa3b, v1
	v_mul_f32_e32 v24, 0xbfb8aa3b, v5
	v_exp_f32_e32 v25, v25
	v_exp_f32_e32 v18, v18
	v_exp_f32_e32 v19, v19
	v_exp_f32_e32 v20, v20
	v_exp_f32_e32 v21, v21
	v_exp_f32_e32 v22, v22
	v_exp_f32_e32 v23, v23
	v_exp_f32_e32 v24, v24
	v_add_f32_e32 v25, 1.0, v25
	v_add_f32_e32 v18, 1.0, v18
	v_add_f32_e32 v19, 1.0, v19
	v_add_f32_e32 v20, 1.0, v20
	v_add_f32_e32 v21, 1.0, v21
	v_add_f32_e32 v22, 1.0, v22
	v_add_f32_e32 v23, 1.0, v23
	v_add_f32_e32 v24, 1.0, v24
	v_rcp_f32_e32 v25, v25
	v_rcp_f32_e32 v18, v18
	v_rcp_f32_e32 v19, v19
	v_rcp_f32_e32 v20, v20
	v_rcp_f32_e32 v21, v21
	v_rcp_f32_e32 v22, v22
	v_rcp_f32_e32 v23, v23
	v_rcp_f32_e32 v24, v24
	v_mul_f32_e32 v3, v3, v25
	v_mul_f32_e32 v17, v17, v18
	v_mul_f32_e32 v9, v9, v19
	v_mul_f32_e32 v13, v13, v20
	v_mul_f32_e32 v11, v11, v21
	v_mul_f32_e32 v15, v15, v22
	v_mul_f32_e32 v1, v1, v23
	v_mul_f32_e32 v5, v5, v24
	v_mul_f32_e32 v3, v2, v3
	s_mov_b64 s[0:1], -1
	v_mul_f32_e32 v16, v16, v17
	v_mul_f32_e32 v8, v8, v9
	v_mul_f32_e32 v9, v12, v13
	v_mul_f32_e32 v10, v10, v11
	v_mul_f32_e32 v11, v14, v15
	v_mul_f32_e32 v12, v0, v1
	v_mul_f32_e32 v4, v4, v5
	v_cvt_pk_bf16_f32 v0, v16, v8
	v_cvt_pk_bf16_f32 v1, v9, v10
	v_cvt_pk_bf16_f32 v2, v11, v12
	v_cvt_pk_bf16_f32 v3, v4, v3
	global_store_dwordx4 v[6:7], v[0:3], off nt
	s_cbranch_vccnz .LBB0_778
	s_andn2_b64 vcc, exec, s[2:3]
	s_cbranch_vccnz .LBB0_777
	s_barrier
	s_branch .LBB0_777

; __device__ __forceinline__ unsigned pk2(float lo, float hi) { return pg8::cvt_pk_bf16(lo, hi); }
;     __device__ __forceinline__ void operator()(const f32x4 (&acc)[2][2][4][2], const pg8::Unit& u, int wr, int wc, int fr, int fq) const {
;         const int row0 = u.pm * 256 + wr * 64 + fr, col0 = u.pn * 256 + wc * 32 + 8 * fq;
; #pragma unroll
;         for (int ai = 0; ai < 2; ++ai)
; #pragma unroll
;             for (int m = 0; m < 4; ++m) {
;                 const int row = row0 + ai * 128 + m * 16; float ss = 0.f;
; #pragma unroll
;                 for (int bj = 0; bj < 2; ++bj) {
;                     const size_t off = (size_t)row * DM + col0 + bj * 128;
;                     float o[8];
;                     if (BASE_BF16) { const u32x4 bw = *(const u32x4*)((const bf16_t*)base + off);
; #pragma unroll
;                         for (int e = 0; e < 4; ++e) { o[2 * e] = __uint_as_float(bw[e] << 16); o[2 * e + 1] = __uint_as_float(bw[e] & 0xffff0000u); } }
;                     else { const f32x4 b0 = *(const f32x4*)((const float*)base + off), b1 = *(const f32x4*)((const float*)base + off + 4);
; #pragma unroll
;                         for (int e = 0; e < 4; ++e) { o[e] = b0[e]; o[4 + e] = b1[e]; } }
; #pragma unroll
;                     for (int n = 0; n < 2; ++n)
; #pragma unroll
;                         for (int e = 0; e < 4; ++e) { const float v = o[4 * n + e] + alpha * acc[ai][bj][m][n][e]; o[4 * n + e] = v; ss += v * v; }
;                     if (OUT_BF16) { u32x4 w; w.x = pk2(o[0], o[1]); w.y = pk2(o[2], o[3]); w.z = pk2(o[4], o[5]); w.w = pk2(o[6], o[7]); *(u32x4*)((bf16_t*)out + off) = w; }
;                     else { *(f32x4*)((float*)out + off) = (f32x4){o[0], o[1], o[2], o[3]}; *(f32x4*)((float*)out + off + 4) = (f32x4){o[4], o[5], o[6], o[7]}; }
.LBB0_865:
	v_lshl_add_u32 v148, s47, 8, v150
	v_lshl_or_b32 v146, s48, 8, v152
	v_ashrrev_i32_e32 v149, 31, v148
	v_ashrrev_i32_e32 v147, 31, v146
	v_lshlrev_b64 v[144:145], 10, v[148:149]
	v_lshl_add_u64 v[144:145], v[144:145], 0, v[146:147]
	v_lshlrev_b64 v[160:161], 1, v[144:145]
	v_lshl_add_u64 v[156:157], s[8:9], 0, v[160:161]
	s_mov_b64 s[98:99], 0x8000
	s_mov_b64 s[100:101], 0x28000
	v_mov_b32_e32 v232, v156
	v_mov_b32_e32 v233, v157
	global_load_dwordx4 v[168:171], v[232:233], off
	global_load_dwordx4 v[172:175], v[232:233], off offset:256
	v_lshl_add_u64 v[232:233], v[232:233], 0, s[98:99]
	global_load_dwordx4 v[176:179], v[232:233], off
	global_load_dwordx4 v[180:183], v[232:233], off offset:256
	v_lshl_add_u64 v[232:233], v[232:233], 0, s[98:99]
	global_load_dwordx4 v[184:187], v[232:233], off
	global_load_dwordx4 v[188:191], v[232:233], off offset:256
	v_lshl_add_u64 v[232:233], v[232:233], 0, s[98:99]
	global_load_dwordx4 v[192:195], v[232:233], off
	global_load_dwordx4 v[196:199], v[232:233], off offset:256
	v_lshl_add_u64 v[232:233], v[232:233], 0, s[100:101]
	global_load_dwordx4 v[200:203], v[232:233], off
	global_load_dwordx4 v[204:207], v[232:233], off offset:256
	v_lshl_add_u64 v[232:233], v[232:233], 0, s[98:99]
	global_load_dwordx4 v[208:211], v[232:233], off
	global_load_dwordx4 v[212:215], v[232:233], off offset:256
	v_lshl_add_u64 v[232:233], v[232:233], 0, s[98:99]
	global_load_dwordx4 v[216:219], v[232:233], off
	global_load_dwordx4 v[220:223], v[232:233], off offset:256
	v_lshl_add_u64 v[232:233], v[232:233], 0, s[98:99]
	global_load_dwordx4 v[224:227], v[232:233], off
	global_load_dwordx4 v[228:231], v[232:233], off offset:256
	v_readlane_b32 s24, v235, 2
	v_readlane_b32 s25, v235, 3
	v_or_b32_e32 v160, 0x100, v160
	v_lshl_add_u64 v[160:161], s[8:9], 0, v[160:161]
	v_lshl_add_u64 v[162:163], v[144:145], 2, s[24:25]
	s_and_b64 vcc, exec, s[0:1]
	s_mov_b64 s[0:1], -1
	v_readlane_b32 s26, v235, 4
	v_readlane_b32 s27, v235, 5
	s_waitcnt vmcnt(15)
	v_mov_b32_e32 v156, v168
	v_mov_b32_e32 v157, v169
	v_mov_b32_e32 v158, v170
	v_mov_b32_e32 v159, v171
	v_lshlrev_b32_e32 v164, 16, v156
	v_and_b32_e32 v165, 0xffff0000, v156
	v_lshlrev_b32_e32 v156, 16, v157
	v_and_b32_e32 v157, 0xffff0000, v157
	v_lshlrev_b32_e32 v166, 16, v158
	v_and_b32_e32 v167, 0xffff0000, v158
	v_lshlrev_b32_e32 v158, 16, v159
	v_and_b32_e32 v159, 0xffff0000, v159
	v_pk_fma_f32 v[124:125], v[124:125], 0.5, v[164:165] op_sel_hi:[1,0,1]
	v_pk_fma_f32 v[126:127], v[126:127], 0.5, v[156:157] op_sel_hi:[1,0,1]
	v_pk_fma_f32 v[120:121], v[120:121], 0.5, v[166:167] op_sel_hi:[1,0,1]
	v_pk_fma_f32 v[122:123], v[122:123], 0.5, v[158:159] op_sel_hi:[1,0,1]
	global_store_dwordx4 v[162:163], v[124:127], off nt
	global_store_dwordx4 v[162:163], v[120:123], off offset:16 nt
	s_nop 0
	v_or_b32_e32 v124, 16, v148
	v_ashrrev_i32_e32 v125, 31, v124
	v_lshlrev_b64 v[124:125], 10, v[124:125]
	v_lshl_add_u64 v[124:125], v[124:125], 0, v[146:147]
	v_lshlrev_b64 v[126:127], 1, v[124:125]
	v_lshl_add_u64 v[156:157], s[8:9], 0, v[126:127]
	v_or_b32_e32 v126, 0x100, v126
	s_waitcnt vmcnt(16)
	v_mov_b32_e32 v120, v172
	v_mov_b32_e32 v121, v173
	v_mov_b32_e32 v122, v174
	v_mov_b32_e32 v123, v175
	v_lshlrev_b32_e32 v158, 16, v120
	v_and_b32_e32 v159, 0xffff0000, v120
	v_lshlrev_b32_e32 v120, 16, v121
	v_and_b32_e32 v121, 0xffff0000, v121
	v_lshlrev_b32_e32 v160, 16, v122
	v_and_b32_e32 v161, 0xffff0000, v122
	v_lshlrev_b32_e32 v122, 16, v123
	v_and_b32_e32 v123, 0xffff0000, v123
	v_pk_fma_f32 v[116:117], v[116:117], 0.5, v[158:159] op_sel_hi:[1,0,1]
	v_pk_fma_f32 v[118:119], v[118:119], 0.5, v[120:121] op_sel_hi:[1,0,1]
	v_pk_fma_f32 v[112:113], v[112:113], 0.5, v[160:161] op_sel_hi:[1,0,1]
	v_pk_fma_f32 v[114:115], v[114:115], 0.5, v[122:123] op_sel_hi:[1,0,1]
	global_store_dwordx4 v[162:163], v[116:119], off offset:512 nt
	global_store_dwordx4 v[162:163], v[112:115], off offset:528 nt
	s_nop 0
	v_lshl_add_u64 v[116:117], v[124:125], 2, s[24:25]
	v_lshl_add_u64 v[118:119], s[8:9], 0, v[126:127]
	s_waitcnt vmcnt(17)
	v_mov_b32_e32 v112, v176
	v_mov_b32_e32 v113, v177
	v_mov_b32_e32 v114, v178
	v_mov_b32_e32 v115, v179
	v_lshlrev_b32_e32 v120, 16, v112
	v_and_b32_e32 v121, 0xffff0000, v112
	v_lshlrev_b32_e32 v112, 16, v113
	v_and_b32_e32 v113, 0xffff0000, v113
	v_lshlrev_b32_e32 v122, 16, v114
	v_and_b32_e32 v123, 0xffff0000, v114
	v_lshlrev_b32_e32 v114, 16, v115
	v_and_b32_e32 v115, 0xffff0000, v115
	v_pk_fma_f32 v[108:109], v[108:109], 0.5, v[120:121] op_sel_hi:[1,0,1]
	v_pk_fma_f32 v[110:111], v[110:111], 0.5, v[112:113] op_sel_hi:[1,0,1]
	v_pk_fma_f32 v[104:105], v[104:105], 0.5, v[122:123] op_sel_hi:[1,0,1]
	v_pk_fma_f32 v[106:107], v[106:107], 0.5, v[114:115] op_sel_hi:[1,0,1]
	global_store_dwordx4 v[116:117], v[108:111], off nt
	global_store_dwordx4 v[116:117], v[104:107], off offset:16 nt
	s_nop 0
	v_or_b32_e32 v108, 32, v148
	v_ashrrev_i32_e32 v109, 31, v108
	v_lshlrev_b64 v[108:109], 10, v[108:109]
	v_lshl_add_u64 v[108:109], v[108:109], 0, v[146:147]
	v_lshlrev_b64 v[110:111], 1, v[108:109]
	v_lshl_add_u64 v[112:113], s[8:9], 0, v[110:111]
	v_or_b32_e32 v110, 0x100, v110
	s_waitcnt vmcnt(18)
	v_mov_b32_e32 v104, v180
	v_mov_b32_e32 v105, v181
	v_mov_b32_e32 v106, v182
	v_mov_b32_e32 v107, v183
	v_lshlrev_b32_e32 v114, 16, v104
	v_and_b32_e32 v115, 0xffff0000, v104
	v_lshlrev_b32_e32 v104, 16, v105
	v_and_b32_e32 v105, 0xffff0000, v105
	v_lshlrev_b32_e32 v118, 16, v106
	v_and_b32_e32 v119, 0xffff0000, v106
	v_lshlrev_b32_e32 v106, 16, v107
	v_and_b32_e32 v107, 0xffff0000, v107
	v_pk_fma_f32 v[100:101], v[100:101], 0.5, v[114:115] op_sel_hi:[1,0,1]
	v_pk_fma_f32 v[102:103], v[102:103], 0.5, v[104:105] op_sel_hi:[1,0,1]
	v_pk_fma_f32 v[96:97], v[96:97], 0.5, v[118:119] op_sel_hi:[1,0,1]
	v_pk_fma_f32 v[98:99], v[98:99], 0.5, v[106:107] op_sel_hi:[1,0,1]
	global_store_dwordx4 v[116:117], v[100:103], off offset:512 nt
	global_store_dwordx4 v[116:117], v[96:99], off offset:528 nt
	s_nop 0
	v_lshl_add_u64 v[100:101], v[108:109], 2, s[24:25]
	v_lshl_add_u64 v[102:103], s[8:9], 0, v[110:111]
	s_waitcnt vmcnt(19)
; __device__ __forceinline__ unsigned pk2(float lo, float hi) { return pg8::cvt_pk_bf16(lo, hi); }
;     __device__ __forceinline__ void operator()(const f32x4 (&acc)[2][2][4][2], const pg8::Unit& u, int wr, int wc, int fr, int fq) const {
;         const int row0 = u.pm * 256 + wr * 64 + fr, col0 = u.pn * 256 + wc * 32 + 8 * fq;
; #pragma unroll
;         for (int ai = 0; ai < 2; ++ai)
; #pragma unroll
;             for (int m = 0; m < 4; ++m) {
;                 const int row = row0 + ai * 128 + m * 16; float ss = 0.f;
; #pragma unroll
;                 for (int bj = 0; bj < 2; ++bj) {
;                     const size_t off = (size_t)row * DM + col0 + bj * 128;
;                     float o[8];
;                     if (BASE_BF16) { const u32x4 bw = *(const u32x4*)((const bf16_t*)base + off);
; #pragma unroll
;                         for (int e = 0; e < 4; ++e) { o[2 * e] = __uint_as_float(bw[e] << 16); o[2 * e + 1] = __uint_as_float(bw[e] & 0xffff0000u); } }
;                     else { const f32x4 b0 = *(const f32x4*)((const float*)base + off), b1 = *(const f32x4*)((const float*)base + off + 4);
; #pragma unroll
;                         for (int e = 0; e < 4; ++e) { o[e] = b0[e]; o[4 + e] = b1[e]; } }
; #pragma unroll
;                     for (int n = 0; n < 2; ++n)
; #pragma unroll
;                         for (int e = 0; e < 4; ++e) { const float v = o[4 * n + e] + alpha * acc[ai][bj][m][n][e]; o[4 * n + e] = v; ss += v * v; }
;                     if (OUT_BF16) { u32x4 w; w.x = pk2(o[0], o[1]); w.y = pk2(o[2], o[3]); w.z = pk2(o[4], o[5]); w.w = pk2(o[6], o[7]); *(u32x4*)((bf16_t*)out + off) = w; }
;                     else { *(f32x4*)((float*)out + off) = (f32x4){o[0], o[1], o[2], o[3]}; *(f32x4*)((float*)out + off + 4) = (f32x4){o[4], o[5], o[6], o[7]}; }
	v_mov_b32_e32 v96, v184
	v_mov_b32_e32 v97, v185
	v_mov_b32_e32 v98, v186
	v_mov_b32_e32 v99, v187
	v_lshlrev_b32_e32 v104, 16, v96
	v_and_b32_e32 v105, 0xffff0000, v96
	v_lshlrev_b32_e32 v96, 16, v97
	v_and_b32_e32 v97, 0xffff0000, v97
	v_lshlrev_b32_e32 v106, 16, v98
	v_and_b32_e32 v107, 0xffff0000, v98
	v_lshlrev_b32_e32 v98, 16, v99
	v_and_b32_e32 v99, 0xffff0000, v99
	v_pk_fma_f32 v[92:93], v[92:93], 0.5, v[104:105] op_sel_hi:[1,0,1]
	v_pk_fma_f32 v[94:95], v[94:95], 0.5, v[96:97] op_sel_hi:[1,0,1]
	v_pk_fma_f32 v[88:89], v[88:89], 0.5, v[106:107] op_sel_hi:[1,0,1]
	v_pk_fma_f32 v[90:91], v[90:91], 0.5, v[98:99] op_sel_hi:[1,0,1]
	global_store_dwordx4 v[100:101], v[92:95], off nt
	global_store_dwordx4 v[100:101], v[88:91], off offset:16 nt
	s_nop 0
	v_or_b32_e32 v92, 48, v148
	v_ashrrev_i32_e32 v93, 31, v92
	v_lshlrev_b64 v[92:93], 10, v[92:93]
	v_lshl_add_u64 v[92:93], v[92:93], 0, v[146:147]
	v_lshlrev_b64 v[94:95], 1, v[92:93]
	v_lshl_add_u64 v[96:97], s[8:9], 0, v[94:95]
	v_or_b32_e32 v94, 0x100, v94
	s_waitcnt vmcnt(20)
	v_mov_b32_e32 v88, v188
	v_mov_b32_e32 v89, v189
	v_mov_b32_e32 v90, v190
	v_mov_b32_e32 v91, v191
	v_lshlrev_b32_e32 v98, 16, v88
	v_and_b32_e32 v99, 0xffff0000, v88
	v_lshlrev_b32_e32 v88, 16, v89
	v_and_b32_e32 v89, 0xffff0000, v89
	v_lshlrev_b32_e32 v102, 16, v90
	v_and_b32_e32 v103, 0xffff0000, v90
	v_lshlrev_b32_e32 v90, 16, v91
	v_and_b32_e32 v91, 0xffff0000, v91
	v_pk_fma_f32 v[84:85], v[84:85], 0.5, v[98:99] op_sel_hi:[1,0,1]
	v_pk_fma_f32 v[86:87], v[86:87], 0.5, v[88:89] op_sel_hi:[1,0,1]
	v_pk_fma_f32 v[80:81], v[80:81], 0.5, v[102:103] op_sel_hi:[1,0,1]
	v_pk_fma_f32 v[82:83], v[82:83], 0.5, v[90:91] op_sel_hi:[1,0,1]
	global_store_dwordx4 v[100:101], v[84:87], off offset:512 nt
	global_store_dwordx4 v[100:101], v[80:83], off offset:528 nt
	s_nop 0
	v_lshl_add_u64 v[84:85], v[92:93], 2, s[24:25]
	v_lshl_add_u64 v[86:87], s[8:9], 0, v[94:95]
	s_waitcnt vmcnt(21)
	v_mov_b32_e32 v80, v192
	v_mov_b32_e32 v81, v193
	v_mov_b32_e32 v82, v194
	v_mov_b32_e32 v83, v195
	v_lshlrev_b32_e32 v88, 16, v80
	v_and_b32_e32 v89, 0xffff0000, v80
	v_lshlrev_b32_e32 v80, 16, v81
	v_and_b32_e32 v81, 0xffff0000, v81
	v_lshlrev_b32_e32 v90, 16, v82
	v_and_b32_e32 v91, 0xffff0000, v82
	v_lshlrev_b32_e32 v82, 16, v83
	v_and_b32_e32 v83, 0xffff0000, v83
	v_pk_fma_f32 v[76:77], v[76:77], 0.5, v[88:89] op_sel_hi:[1,0,1]
	v_pk_fma_f32 v[78:79], v[78:79], 0.5, v[80:81] op_sel_hi:[1,0,1]
	v_pk_fma_f32 v[72:73], v[72:73], 0.5, v[90:91] op_sel_hi:[1,0,1]
	v_pk_fma_f32 v[74:75], v[74:75], 0.5, v[82:83] op_sel_hi:[1,0,1]
	global_store_dwordx4 v[84:85], v[76:79], off nt
	global_store_dwordx4 v[84:85], v[72:75], off offset:16 nt
	s_nop 0
	v_lshl_add_u64 v[76:77], v[144:145], 0, s[12:13]
	v_lshlrev_b64 v[78:79], 1, v[76:77]
	v_lshl_add_u64 v[80:81], s[8:9], 0, v[78:79]
	v_or_b32_e32 v78, 0x100, v78
	s_waitcnt vmcnt(22)
	v_mov_b32_e32 v72, v196
	v_mov_b32_e32 v73, v197
	v_mov_b32_e32 v74, v198
	v_mov_b32_e32 v75, v199
	v_lshlrev_b32_e32 v82, 16, v72
	v_and_b32_e32 v83, 0xffff0000, v72
	v_lshlrev_b32_e32 v72, 16, v73
	v_and_b32_e32 v73, 0xffff0000, v73
	v_lshlrev_b32_e32 v86, 16, v74
	v_and_b32_e32 v87, 0xffff0000, v74
	v_lshlrev_b32_e32 v74, 16, v75
	v_and_b32_e32 v75, 0xffff0000, v75
	v_pk_fma_f32 v[68:69], v[68:69], 0.5, v[82:83] op_sel_hi:[1,0,1]
	v_pk_fma_f32 v[70:71], v[70:71], 0.5, v[72:73] op_sel_hi:[1,0,1]
	v_pk_fma_f32 v[64:65], v[64:65], 0.5, v[86:87] op_sel_hi:[1,0,1]
	v_pk_fma_f32 v[66:67], v[66:67], 0.5, v[74:75] op_sel_hi:[1,0,1]
	global_store_dwordx4 v[84:85], v[68:71], off offset:512 nt
	global_store_dwordx4 v[84:85], v[64:67], off offset:528 nt
	s_nop 0
	v_lshl_add_u64 v[68:69], v[76:77], 2, s[24:25]
	v_lshl_add_u64 v[70:71], s[8:9], 0, v[78:79]
	s_waitcnt vmcnt(23)
	v_mov_b32_e32 v64, v200
	v_mov_b32_e32 v65, v201
	v_mov_b32_e32 v66, v202
	v_mov_b32_e32 v67, v203
	v_lshlrev_b32_e32 v72, 16, v64
	v_and_b32_e32 v73, 0xffff0000, v64
	v_lshlrev_b32_e32 v64, 16, v65
	v_and_b32_e32 v65, 0xffff0000, v65
	v_lshlrev_b32_e32 v74, 16, v66
	v_and_b32_e32 v75, 0xffff0000, v66
	v_lshlrev_b32_e32 v66, 16, v67
	v_and_b32_e32 v67, 0xffff0000, v67
	v_pk_fma_f32 v[60:61], v[60:61], 0.5, v[72:73] op_sel_hi:[1,0,1]
	v_pk_fma_f32 v[62:63], v[62:63], 0.5, v[64:65] op_sel_hi:[1,0,1]
	v_pk_fma_f32 v[56:57], v[56:57], 0.5, v[74:75] op_sel_hi:[1,0,1]
	v_pk_fma_f32 v[58:59], v[58:59], 0.5, v[66:67] op_sel_hi:[1,0,1]
	global_store_dwordx4 v[68:69], v[60:63], off nt
	global_store_dwordx4 v[68:69], v[56:59], off offset:16 nt
	s_nop 0
	v_lshl_add_u64 v[60:61], v[144:145], 0, s[14:15]
	v_lshlrev_b64 v[62:63], 1, v[60:61]
	v_lshl_add_u64 v[64:65], s[8:9], 0, v[62:63]
	v_or_b32_e32 v62, 0x100, v62
	s_waitcnt vmcnt(24)
	v_mov_b32_e32 v56, v204
	v_mov_b32_e32 v57, v205
	v_mov_b32_e32 v58, v206
	v_mov_b32_e32 v59, v207
	v_lshlrev_b32_e32 v66, 16, v56
	v_and_b32_e32 v67, 0xffff0000, v56
	v_lshlrev_b32_e32 v56, 16, v57
	v_and_b32_e32 v57, 0xffff0000, v57
	v_lshlrev_b32_e32 v70, 16, v58
	v_and_b32_e32 v71, 0xffff0000, v58
	v_lshlrev_b32_e32 v58, 16, v59
	v_and_b32_e32 v59, 0xffff0000, v59
	v_pk_fma_f32 v[52:53], v[52:53], 0.5, v[66:67] op_sel_hi:[1,0,1]
	v_pk_fma_f32 v[54:55], v[54:55], 0.5, v[56:57] op_sel_hi:[1,0,1]
	v_pk_fma_f32 v[48:49], v[48:49], 0.5, v[70:71] op_sel_hi:[1,0,1]
	v_pk_fma_f32 v[50:51], v[50:51], 0.5, v[58:59] op_sel_hi:[1,0,1]
	global_store_dwordx4 v[68:69], v[52:55], off offset:512 nt
	global_store_dwordx4 v[68:69], v[48:51], off offset:528 nt
	s_nop 0
	v_lshl_add_u64 v[52:53], v[60:61], 2, s[24:25]
	v_lshl_add_u64 v[54:55], s[8:9], 0, v[62:63]
	s_waitcnt vmcnt(25)
; __device__ __forceinline__ unsigned pk2(float lo, float hi) { return pg8::cvt_pk_bf16(lo, hi); }
;     __device__ __forceinline__ void operator()(const f32x4 (&acc)[2][2][4][2], const pg8::Unit& u, int wr, int wc, int fr, int fq) const {
;         const int row0 = u.pm * 256 + wr * 64 + fr, col0 = u.pn * 256 + wc * 32 + 8 * fq;
; #pragma unroll
;         for (int ai = 0; ai < 2; ++ai)
; #pragma unroll
;             for (int m = 0; m < 4; ++m) {
;                 const int row = row0 + ai * 128 + m * 16; float ss = 0.f;
; #pragma unroll
;                 for (int bj = 0; bj < 2; ++bj) {
;                     const size_t off = (size_t)row * DM + col0 + bj * 128;
;                     float o[8];
;                     if (BASE_BF16) { const u32x4 bw = *(const u32x4*)((const bf16_t*)base + off);
; #pragma unroll
;                         for (int e = 0; e < 4; ++e) { o[2 * e] = __uint_as_float(bw[e] << 16); o[2 * e + 1] = __uint_as_float(bw[e] & 0xffff0000u); } }
;                     else { const f32x4 b0 = *(const f32x4*)((const float*)base + off), b1 = *(const f32x4*)((const float*)base + off + 4);
; #pragma unroll
;                         for (int e = 0; e < 4; ++e) { o[e] = b0[e]; o[4 + e] = b1[e]; } }
; #pragma unroll
;                     for (int n = 0; n < 2; ++n)
; #pragma unroll
;                         for (int e = 0; e < 4; ++e) { const float v = o[4 * n + e] + alpha * acc[ai][bj][m][n][e]; o[4 * n + e] = v; ss += v * v; }
;                     if (OUT_BF16) { u32x4 w; w.x = pk2(o[0], o[1]); w.y = pk2(o[2], o[3]); w.z = pk2(o[4], o[5]); w.w = pk2(o[6], o[7]); *(u32x4*)((bf16_t*)out + off) = w; }
;                     else { *(f32x4*)((float*)out + off) = (f32x4){o[0], o[1], o[2], o[3]}; *(f32x4*)((float*)out + off + 4) = (f32x4){o[4], o[5], o[6], o[7]}; }
	v_mov_b32_e32 v48, v208
	v_mov_b32_e32 v49, v209
	v_mov_b32_e32 v50, v210
	v_mov_b32_e32 v51, v211
	v_lshlrev_b32_e32 v56, 16, v48
	v_and_b32_e32 v57, 0xffff0000, v48
	v_lshlrev_b32_e32 v48, 16, v49
	v_and_b32_e32 v49, 0xffff0000, v49
	v_lshlrev_b32_e32 v58, 16, v50
	v_and_b32_e32 v59, 0xffff0000, v50
	v_lshlrev_b32_e32 v50, 16, v51
	v_and_b32_e32 v51, 0xffff0000, v51
	v_pk_fma_f32 v[44:45], v[44:45], 0.5, v[56:57] op_sel_hi:[1,0,1]
	v_pk_fma_f32 v[46:47], v[46:47], 0.5, v[48:49] op_sel_hi:[1,0,1]
	v_pk_fma_f32 v[40:41], v[40:41], 0.5, v[58:59] op_sel_hi:[1,0,1]
	v_pk_fma_f32 v[42:43], v[42:43], 0.5, v[50:51] op_sel_hi:[1,0,1]
	global_store_dwordx4 v[52:53], v[44:47], off nt
	global_store_dwordx4 v[52:53], v[40:43], off offset:16 nt
	s_nop 0
	v_lshl_add_u64 v[44:45], v[144:145], 0, s[16:17]
	v_lshlrev_b64 v[46:47], 1, v[44:45]
	v_lshl_add_u64 v[48:49], s[8:9], 0, v[46:47]
	v_or_b32_e32 v46, 0x100, v46
	s_waitcnt vmcnt(26)
	v_mov_b32_e32 v40, v212
	v_mov_b32_e32 v41, v213
	v_mov_b32_e32 v42, v214
	v_mov_b32_e32 v43, v215
	v_lshlrev_b32_e32 v50, 16, v40
	v_and_b32_e32 v51, 0xffff0000, v40
	v_lshlrev_b32_e32 v40, 16, v41
	v_and_b32_e32 v41, 0xffff0000, v41
	v_lshlrev_b32_e32 v54, 16, v42
	v_and_b32_e32 v55, 0xffff0000, v42
	v_lshlrev_b32_e32 v42, 16, v43
	v_and_b32_e32 v43, 0xffff0000, v43
	v_pk_fma_f32 v[36:37], v[36:37], 0.5, v[50:51] op_sel_hi:[1,0,1]
	v_pk_fma_f32 v[38:39], v[38:39], 0.5, v[40:41] op_sel_hi:[1,0,1]
	v_pk_fma_f32 v[32:33], v[32:33], 0.5, v[54:55] op_sel_hi:[1,0,1]
	v_pk_fma_f32 v[34:35], v[34:35], 0.5, v[42:43] op_sel_hi:[1,0,1]
	global_store_dwordx4 v[52:53], v[36:39], off offset:512 nt
	global_store_dwordx4 v[52:53], v[32:35], off offset:528 nt
	s_nop 0
	v_lshl_add_u64 v[36:37], v[44:45], 2, s[24:25]
	v_lshl_add_u64 v[38:39], s[8:9], 0, v[46:47]
	s_waitcnt vmcnt(27)
	v_mov_b32_e32 v32, v216
	v_mov_b32_e32 v33, v217
	v_mov_b32_e32 v34, v218
	v_mov_b32_e32 v35, v219
	v_lshlrev_b32_e32 v40, 16, v32
	v_and_b32_e32 v41, 0xffff0000, v32
	v_lshlrev_b32_e32 v32, 16, v33
	v_and_b32_e32 v33, 0xffff0000, v33
	v_lshlrev_b32_e32 v42, 16, v34
	v_and_b32_e32 v43, 0xffff0000, v34
	v_lshlrev_b32_e32 v34, 16, v35
	v_and_b32_e32 v35, 0xffff0000, v35
	v_pk_fma_f32 v[28:29], v[28:29], 0.5, v[40:41] op_sel_hi:[1,0,1]
	v_pk_fma_f32 v[30:31], v[30:31], 0.5, v[32:33] op_sel_hi:[1,0,1]
	v_pk_fma_f32 v[24:25], v[24:25], 0.5, v[42:43] op_sel_hi:[1,0,1]
	v_pk_fma_f32 v[26:27], v[26:27], 0.5, v[34:35] op_sel_hi:[1,0,1]
	global_store_dwordx4 v[36:37], v[28:31], off nt
	global_store_dwordx4 v[36:37], v[24:27], off offset:16 nt
	s_nop 0
	v_lshl_add_u64 v[28:29], v[144:145], 0, s[18:19]
	v_lshlrev_b64 v[30:31], 1, v[28:29]
	v_lshl_add_u64 v[32:33], s[8:9], 0, v[30:31]
	v_or_b32_e32 v30, 0x100, v30
	s_waitcnt vmcnt(28)
	v_mov_b32_e32 v24, v220
	v_mov_b32_e32 v25, v221
	v_mov_b32_e32 v26, v222
	v_mov_b32_e32 v27, v223
	v_lshlrev_b32_e32 v34, 16, v24
	v_and_b32_e32 v35, 0xffff0000, v24
	v_lshlrev_b32_e32 v24, 16, v25
	v_and_b32_e32 v25, 0xffff0000, v25
	v_lshlrev_b32_e32 v38, 16, v26
	v_and_b32_e32 v39, 0xffff0000, v26
	v_lshlrev_b32_e32 v26, 16, v27
	v_and_b32_e32 v27, 0xffff0000, v27
	v_pk_fma_f32 v[20:21], v[20:21], 0.5, v[34:35] op_sel_hi:[1,0,1]
	v_pk_fma_f32 v[22:23], v[22:23], 0.5, v[24:25] op_sel_hi:[1,0,1]
	v_pk_fma_f32 v[16:17], v[16:17], 0.5, v[38:39] op_sel_hi:[1,0,1]
	v_pk_fma_f32 v[18:19], v[18:19], 0.5, v[26:27] op_sel_hi:[1,0,1]
	global_store_dwordx4 v[36:37], v[20:23], off offset:512 nt
	global_store_dwordx4 v[36:37], v[16:19], off offset:528 nt
	s_nop 0
	v_lshl_add_u64 v[20:21], v[28:29], 2, s[24:25]
	v_lshl_add_u64 v[22:23], s[8:9], 0, v[30:31]
	s_waitcnt vmcnt(29)
	v_mov_b32_e32 v16, v224
	v_mov_b32_e32 v17, v225
	v_mov_b32_e32 v18, v226
	v_mov_b32_e32 v19, v227
	v_lshlrev_b32_e32 v24, 16, v16
	v_and_b32_e32 v25, 0xffff0000, v16
	v_lshlrev_b32_e32 v16, 16, v17
	v_and_b32_e32 v17, 0xffff0000, v17
	v_lshlrev_b32_e32 v26, 16, v18
	v_and_b32_e32 v27, 0xffff0000, v18
	v_lshlrev_b32_e32 v18, 16, v19
	v_and_b32_e32 v19, 0xffff0000, v19
	v_pk_fma_f32 v[12:13], v[12:13], 0.5, v[24:25] op_sel_hi:[1,0,1]
	v_pk_fma_f32 v[14:15], v[14:15], 0.5, v[16:17] op_sel_hi:[1,0,1]
	v_pk_fma_f32 v[8:9], v[8:9], 0.5, v[26:27] op_sel_hi:[1,0,1]
	v_pk_fma_f32 v[10:11], v[10:11], 0.5, v[18:19] op_sel_hi:[1,0,1]
	global_store_dwordx4 v[20:21], v[12:15], off nt
	global_store_dwordx4 v[20:21], v[8:11], off offset:16 nt
	s_nop 0
	s_waitcnt vmcnt(30)
	v_mov_b32_e32 v8, v228
	v_mov_b32_e32 v9, v229
	v_mov_b32_e32 v10, v230
	v_mov_b32_e32 v11, v231
	v_lshlrev_b32_e32 v12, 16, v8
	v_and_b32_e32 v13, 0xffff0000, v8
	v_lshlrev_b32_e32 v8, 16, v9
	v_and_b32_e32 v9, 0xffff0000, v9
	v_lshlrev_b32_e32 v14, 16, v10
	v_and_b32_e32 v15, 0xffff0000, v10
	v_lshlrev_b32_e32 v10, 16, v11
	v_and_b32_e32 v11, 0xffff0000, v11
	v_pk_fma_f32 v[4:5], v[4:5], 0.5, v[12:13] op_sel_hi:[1,0,1]
	v_pk_fma_f32 v[6:7], v[6:7], 0.5, v[8:9] op_sel_hi:[1,0,1]
	v_pk_fma_f32 v[0:1], v[0:1], 0.5, v[14:15] op_sel_hi:[1,0,1]
	v_pk_fma_f32 v[2:3], v[2:3], 0.5, v[10:11] op_sel_hi:[1,0,1]
	global_store_dwordx4 v[20:21], v[4:7], off offset:512 nt
	global_store_dwordx4 v[20:21], v[0:3], off offset:528 nt
	s_cbranch_vccnz .LBB0_850
	s_andn2_b64 vcc, exec, s[2:3]
	s_cbranch_vccnz .LBB0_849
	s_barrier
	s_branch .LBB0_849
